# Gray MFMA order; per-segment s_setprio flips removed, one static s_setprio 1 for waves 4-7 around the K-loops
# speedup vs baseline: 1.0069x; 1.0069x over previous
; #define PG8_STAGE(bufoff, gbase, voff) do { _Pragma("unroll") for (int _i = 0; _i < 2; ++_i) \
;         __builtin_amdgcn_global_load_lds((const unsigned*)((const char*)(gbase) + (voff)[_i]), (PG8_LAS unsigned*)(lds + (bufoff) + ldsw + _i * 8192), 16, 0, 0); } while (0)
; #define PG8_LDA(dst, b, h) do { _Pragma("unroll") for (int m = 0; m < 4; ++m) _Pragma("unroll") for (int k = 0; k < 2; ++k) dst[m][k] = *(const PG8_LAS bf16x8*)(lds + PG8_SA(b, h) + aoff + m * 2048 + k * 1024); } while (0)
; #define PG8_LDB(dst, b, h) do { _Pragma("unroll") for (int n = 0; n < 2; ++n) _Pragma("unroll") for (int k = 0; k < 2; ++k) dst[n][k] = *(const PG8_LAS bf16x8*)(lds + PG8_SB(b, h) + boff + n * 2048 + k * 1024); } while (0)
; #define PG8_MMA(ai, bj, At, Bt) do { __builtin_amdgcn_s_setprio(1); _Pragma("unroll") for (int m = 0; m < 4; ++m) _Pragma("unroll") for (int n = 0; n < 2; ++n) _Pragma("unroll") for (int k = 0; k < 2; ++k) \
;         acc[ai][bj][m][n] = __builtin_amdgcn_mfma_f32_16x16x32_bf16(Bt[n][k], At[m][k], acc[ai][bj][m][n], 0, 0, 0); __builtin_amdgcn_s_setprio(0); } while (0)
; #define PG8_WAIT_V(n) asm volatile("s_waitcnt vmcnt(" #n ")" ::: "memory")
; #define PG8_WAIT_L(n) asm volatile("s_waitcnt lgkmcnt(" #n ")" ::: "memory")
; #define PG8_BAR __builtin_amdgcn_s_barrier()
; template <class Epi, class Sched, bool ALIGN_EPI = false, bool SP2 = false>
; __device__ __forceinline__ void gemm_phase(PG8_LAS unsigned char* lds, const Gemm g, const Sched& S, const Epi& E) {
;     ...
;         const char* nA = has_next ? (const char*)g.A + (size_t)nxt.pm * tstep : cA; const char* nB = has_next ? (const char*)g.Bt + (size_t)nxt.pn * tstep : cB;
;         for (int t = 0; t < nt; t += 2) {
;             const bool last = (t == nt - 2);
;             const char* a1 = cA + (size_t)(t + 1) * kstepA;
;             const char* a2 = last ? nA : cA + (size_t)(t + 2) * kstepA; const char* b2 = last ? nB : cB + (size_t)(t + 2) * kstep;
;             const char* a3 = a2 + kstepA; const char* b3 = b2 + kstep;
;             if (last && has_next) S.a_ready(nxt);
;             if constexpr (SP2) {
;             PG8_LDB(B0, 0, 0); PG8_LDB(B1, 0, 1); PG8_SCHED; PG8_LDA(At, 0, 0); PG8_STAGE(PG8_SA(1, 1), a1 + hstep, voffA);
;             PG8_WAIT_V(8); PG8_WAIT_L(0); PG8_BAR; PG8_MMA(0, 0, At, B0); PG8_MMA(0, 1, At, B1); PG8_BAR; PG8_SCHED;
.LBB0_237:
	s_ashr_i32 s11, s10, 31
	s_lshl_b64 s[2:3], s[10:11], 19
	s_add_u32 s12, s52, s2
	s_addc_u32 s13, s53, s3
	s_and_b64 s[2:3], s[40:41], exec
	s_cselect_b32 s11, s13, s25
	s_cselect_b32 s67, s12, s24
	s_ashr_i32 s9, s8, 31
	s_lshl_b64 s[2:3], s[8:9], 19
	s_add_u32 s44, s54, s2
	s_addc_u32 s45, s55, s3
	s_and_b64 s[2:3], s[40:41], exec
	s_cselect_b32 s9, s45, s27
	s_cselect_b32 s68, s44, s26
	s_add_u32 s69, s26, 0x100
	v_mov_b64_e32 v[2:3], 0
	v_mov_b64_e32 v[4:5], 0
	v_mov_b64_e32 v[6:7], 0
	v_mov_b64_e32 v[8:9], 0
	v_mov_b64_e32 v[10:11], 0
	v_mov_b64_e32 v[12:13], 0
	v_mov_b64_e32 v[14:15], 0
	v_mov_b64_e32 v[16:17], 0
	v_mov_b64_e32 v[18:19], 0
	v_mov_b64_e32 v[20:21], 0
	v_mov_b64_e32 v[22:23], 0
	v_mov_b64_e32 v[24:25], 0
	v_mov_b64_e32 v[26:27], 0
	v_mov_b64_e32 v[28:29], 0
	v_mov_b64_e32 v[30:31], 0
	v_mov_b64_e32 v[32:33], 0
	v_mov_b64_e32 v[34:35], 0
	v_mov_b64_e32 v[36:37], 0
	v_mov_b64_e32 v[38:39], 0
	v_mov_b64_e32 v[40:41], 0
	v_mov_b64_e32 v[42:43], 0
	v_mov_b64_e32 v[44:45], 0
	v_mov_b64_e32 v[46:47], 0
	v_mov_b64_e32 v[48:49], 0
	v_mov_b64_e32 v[50:51], 0
	v_mov_b64_e32 v[52:53], 0
	v_mov_b64_e32 v[54:55], 0
	v_mov_b64_e32 v[56:57], 0
	v_mov_b64_e32 v[58:59], 0
	v_mov_b64_e32 v[60:61], 0
	v_mov_b64_e32 v[62:63], 0
	v_mov_b64_e32 v[64:65], 0
	v_mov_b64_e32 v[66:67], 0
	v_mov_b64_e32 v[68:69], 0
	v_mov_b64_e32 v[70:71], 0
	v_mov_b64_e32 v[72:73], 0
	v_mov_b64_e32 v[74:75], 0
	v_mov_b64_e32 v[76:77], 0
	v_mov_b64_e32 v[78:79], 0
	v_mov_b64_e32 v[80:81], 0
	v_mov_b64_e32 v[82:83], 0
	v_mov_b64_e32 v[84:85], 0
	v_mov_b64_e32 v[86:87], 0
	v_mov_b64_e32 v[88:89], 0
	v_mov_b64_e32 v[90:91], 0
	v_mov_b64_e32 v[92:93], 0
	v_mov_b64_e32 v[94:95], 0
	v_mov_b64_e32 v[96:97], 0
	v_mov_b64_e32 v[98:99], 0
	v_mov_b64_e32 v[100:101], 0
	v_mov_b64_e32 v[102:103], 0
	v_mov_b64_e32 v[104:105], 0
	v_mov_b64_e32 v[106:107], 0
	v_mov_b64_e32 v[108:109], 0
	v_mov_b64_e32 v[110:111], 0
	v_mov_b64_e32 v[112:113], 0
	v_mov_b64_e32 v[114:115], 0
	v_mov_b64_e32 v[116:117], 0
	v_mov_b64_e32 v[118:119], 0
	v_mov_b64_e32 v[120:121], 0
	v_mov_b64_e32 v[122:123], 0
	v_mov_b64_e32 v[124:125], 0
	v_mov_b64_e32 v[126:127], 0
	v_mov_b64_e32 v[128:129], 0
	s_addc_u32 s70, s27, 0
	s_mov_b32 s71, -2
	s_and_b64 vcc, exec, s[6:7]
	s_cbranch_vccnz .Lp1_skip_1
	s_setprio 1
.Lp1_skip_1:
.LBB0_238:
	s_add_u32 s2, s24, 0x8000
	s_addc_u32 s3, s25, 0
	s_cmp_eq_u32 s71, 12
	s_cselect_b32 s46, s67, s2
	s_cselect_b32 s47, s11, s3
	s_cselect_b32 s42, s68, s69
	s_cselect_b32 s43, s9, s70
	s_add_u32 s26, s46, 0x4000
	s_addc_u32 s27, s47, 0
	v_add_u32_e32 v148, s76, v150
	s_add_i32 s72, 0, 0x14000
	ds_read_b128 v[144:147], v148
	ds_read_b128 v[160:163], v148 offset:1024
	ds_read_b128 v[164:167], v148 offset:2048
	ds_read_b128 v[168:171], v148 offset:3072
	v_add_u32_e32 v148, s72, v150
	ds_read_b128 v[172:175], v148
	ds_read_b128 v[176:179], v148 offset:1024
	ds_read_b128 v[180:183], v148 offset:2048
	ds_read_b128 v[184:187], v148 offset:3072
	v_lshl_add_u64 v[148:149], s[24:25], 0, v[142:143]
	s_add_i32 m0, s23, 0xc000
	ds_read_b128 v[188:191], v152
	ds_read_b128 v[206:209], v152 offset:1024
	ds_read_b128 v[210:213], v152 offset:2048
	ds_read_b128 v[214:217], v152 offset:3072
	ds_read_b128 v[218:221], v152 offset:4096
	ds_read_b128 v[222:225], v152 offset:5120
	ds_read_b128 v[226:229], v152 offset:6144
	ds_read_b128 v[230:233], v152 offset:7168
	global_load_lds_dwordx4 v[148:149], off
	v_lshl_add_u64 v[148:149], s[24:25], 0, v[140:141]
	s_add_i32 m0, s23, 0xe000
	s_nop 0
	global_load_lds_dwordx4 v[148:149], off
	s_waitcnt vmcnt(8)
	s_waitcnt lgkmcnt(0)
	s_barrier
	s_waitcnt lgkmcnt(0)
	v_mfma_f32_16x16x32_bf16 v[126:129], v[144:147], v[188:191], v[126:129]
	v_mfma_f32_16x16x32_bf16 v[126:129], v[160:163], v[206:209], v[126:129]
	v_mfma_f32_16x16x32_bf16 v[122:125], v[168:171], v[206:209], v[122:125]
	v_mfma_f32_16x16x32_bf16 v[122:125], v[164:167], v[188:191], v[122:125]
	v_mfma_f32_16x16x32_bf16 v[106:109], v[164:167], v[210:213], v[106:109]
	v_mfma_f32_16x16x32_bf16 v[106:109], v[168:171], v[214:217], v[106:109]
	v_mfma_f32_16x16x32_bf16 v[110:113], v[160:163], v[214:217], v[110:113]
	v_mfma_f32_16x16x32_bf16 v[110:113], v[144:147], v[210:213], v[110:113]
	v_mfma_f32_16x16x32_bf16 v[94:97], v[144:147], v[218:221], v[94:97]
	v_mfma_f32_16x16x32_bf16 v[94:97], v[160:163], v[222:225], v[94:97]
	v_mfma_f32_16x16x32_bf16 v[90:93], v[168:171], v[222:225], v[90:93]
	v_mfma_f32_16x16x32_bf16 v[90:93], v[164:167], v[218:221], v[90:93]
	v_mfma_f32_16x16x32_bf16 v[74:77], v[164:167], v[226:229], v[74:77]
	v_mfma_f32_16x16x32_bf16 v[74:77], v[168:171], v[230:233], v[74:77]
	v_mfma_f32_16x16x32_bf16 v[78:81], v[160:163], v[230:233], v[78:81]
	v_mfma_f32_16x16x32_bf16 v[78:81], v[144:147], v[226:229], v[78:81]
	v_mfma_f32_16x16x32_bf16 v[118:121], v[172:175], v[188:191], v[118:121]
	v_mfma_f32_16x16x32_bf16 v[118:121], v[176:179], v[206:209], v[118:121]
	v_mfma_f32_16x16x32_bf16 v[114:117], v[184:187], v[206:209], v[114:117]
	v_mfma_f32_16x16x32_bf16 v[114:117], v[180:183], v[188:191], v[114:117]
	v_mfma_f32_16x16x32_bf16 v[98:101], v[180:183], v[210:213], v[98:101]
	v_mfma_f32_16x16x32_bf16 v[98:101], v[184:187], v[214:217], v[98:101]
	v_mfma_f32_16x16x32_bf16 v[102:105], v[176:179], v[214:217], v[102:105]
	v_mfma_f32_16x16x32_bf16 v[102:105], v[172:175], v[210:213], v[102:105]
	v_mfma_f32_16x16x32_bf16 v[86:89], v[172:175], v[218:221], v[86:89]
	v_mfma_f32_16x16x32_bf16 v[86:89], v[176:179], v[222:225], v[86:89]
	v_mfma_f32_16x16x32_bf16 v[82:85], v[184:187], v[222:225], v[82:85]
	v_mfma_f32_16x16x32_bf16 v[82:85], v[180:183], v[218:221], v[82:85]
	v_mfma_f32_16x16x32_bf16 v[66:69], v[180:183], v[226:229], v[66:69]
	v_mfma_f32_16x16x32_bf16 v[66:69], v[184:187], v[230:233], v[66:69]
	v_mfma_f32_16x16x32_bf16 v[70:73], v[176:179], v[230:233], v[70:73]
	v_mfma_f32_16x16x32_bf16 v[70:73], v[172:175], v[226:229], v[70:73]
	s_barrier
; #define PG8_STAGE(bufoff, gbase, voff) do { _Pragma("unroll") for (int _i = 0; _i < 2; ++_i) \
;         __builtin_amdgcn_global_load_lds((const unsigned*)((const char*)(gbase) + (voff)[_i]), (PG8_LAS unsigned*)(lds + (bufoff) + ldsw + _i * 8192), 16, 0, 0); } while (0)
; #define PG8_LDA(dst, b, h) do { _Pragma("unroll") for (int m = 0; m < 4; ++m) _Pragma("unroll") for (int k = 0; k < 2; ++k) dst[m][k] = *(const PG8_LAS bf16x8*)(lds + PG8_SA(b, h) + aoff + m * 2048 + k * 1024); } while (0)
; #define PG8_LDB(dst, b, h) do { _Pragma("unroll") for (int n = 0; n < 2; ++n) _Pragma("unroll") for (int k = 0; k < 2; ++k) dst[n][k] = *(const PG8_LAS bf16x8*)(lds + PG8_SB(b, h) + boff + n * 2048 + k * 1024); } while (0)
; #define PG8_MMA(ai, bj, At, Bt) do { __builtin_amdgcn_s_setprio(1); _Pragma("unroll") for (int m = 0; m < 4; ++m) _Pragma("unroll") for (int n = 0; n < 2; ++n) _Pragma("unroll") for (int k = 0; k < 2; ++k) \
;         acc[ai][bj][m][n] = __builtin_amdgcn_mfma_f32_16x16x32_bf16(Bt[n][k], At[m][k], acc[ai][bj][m][n], 0, 0, 0); __builtin_amdgcn_s_setprio(0); } while (0)
; #define PG8_WAIT_V(n) asm volatile("s_waitcnt vmcnt(" #n ")" ::: "memory")
; #define PG8_WAIT_L(n) asm volatile("s_waitcnt lgkmcnt(" #n ")" ::: "memory")
; #define PG8_BAR __builtin_amdgcn_s_barrier()
; #define PG8_SCHED __builtin_amdgcn_sched_barrier(0)
; template <class Epi, class Sched, bool ALIGN_EPI = false, bool SP2 = false>
; __device__ __forceinline__ void gemm_phase(PG8_LAS unsigned char* lds, const Gemm g, const Sched& S, const Epi& E) {
;     ...
;             PG8_LDA(At, 0, 1); PG8_STAGE(PG8_SB(0, 0), b2, voffB); PG8_STAGE(PG8_SB(0, 1), b2 + hstep, voffB); PG8_STAGE(PG8_SA(0, 0), a2, voffA);
;             PG8_WAIT_V(8); PG8_WAIT_L(0); PG8_BAR; PG8_MMA(1, 0, At, B0); PG8_MMA(1, 1, At, B1); PG8_BAR; PG8_SCHED;
;             PG8_LDB(B0, 1, 0); PG8_LDB(B1, 1, 1); PG8_SCHED; PG8_LDA(At, 1, 0); PG8_STAGE(PG8_SA(0, 1), a2 + hstep, voffA);
;             PG8_WAIT_V(8); PG8_WAIT_L(0); PG8_BAR; PG8_MMA(0, 0, At, B0); PG8_MMA(0, 1, At, B1); PG8_BAR; PG8_SCHED;
	s_add_i32 s24, s76, s51
	v_lshl_add_u64 v[148:149], s[42:43], 0, v[132:133]
	s_mov_b32 m0, s24
	ds_read_b128 v[188:191], v152 offset:16384
	ds_read_b128 v[206:209], v152 offset:17408
	ds_read_b128 v[210:213], v152 offset:18432
	ds_read_b128 v[214:217], v152 offset:19456
	ds_read_b128 v[218:221], v152 offset:20480
	ds_read_b128 v[222:225], v152 offset:21504
	ds_read_b128 v[226:229], v152 offset:22528
	ds_read_b128 v[230:233], v152 offset:23552
	global_load_lds_dwordx4 v[148:149], off
	s_add_i32 m0, s24, 0x2000
	s_add_u32 s24, s42, 0x40000
	v_lshl_add_u64 v[234:235], s[42:43], 0, v[136:137]
	s_addc_u32 s25, s43, 0
	s_add_i32 s72, s72, s51
	global_load_lds_dwordx4 v[234:235], off
	v_lshl_add_u64 v[236:237], s[24:25], 0, v[132:133]
	s_mov_b32 m0, s72
	s_nop 0
	global_load_lds_dwordx4 v[236:237], off
	v_lshl_add_u64 v[236:237], s[24:25], 0, v[136:137]
	s_add_i32 m0, s72, 0x2000
	s_nop 0
	global_load_lds_dwordx4 v[236:237], off
	v_lshl_add_u64 v[236:237], s[46:47], 0, v[130:131]
	s_mov_b32 m0, s23
	s_nop 0
	global_load_lds_dwordx4 v[236:237], off
	v_lshl_add_u64 v[236:237], s[46:47], 0, v[134:135]
	s_mov_b32 m0, s56
	s_nop 0
	global_load_lds_dwordx4 v[236:237], off
	s_waitcnt vmcnt(8)
	s_waitcnt lgkmcnt(0)
	s_barrier
	s_waitcnt lgkmcnt(0)
	v_mfma_f32_16x16x32_bf16 v[62:65], v[144:147], v[188:191], v[62:65]
	v_mfma_f32_16x16x32_bf16 v[62:65], v[160:163], v[206:209], v[62:65]
	v_mfma_f32_16x16x32_bf16 v[58:61], v[168:171], v[206:209], v[58:61]
	v_mfma_f32_16x16x32_bf16 v[58:61], v[164:167], v[188:191], v[58:61]
	v_mfma_f32_16x16x32_bf16 v[42:45], v[164:167], v[210:213], v[42:45]
	v_mfma_f32_16x16x32_bf16 v[42:45], v[168:171], v[214:217], v[42:45]
	v_mfma_f32_16x16x32_bf16 v[46:49], v[160:163], v[214:217], v[46:49]
	v_mfma_f32_16x16x32_bf16 v[46:49], v[144:147], v[210:213], v[46:49]
	v_mfma_f32_16x16x32_bf16 v[30:33], v[144:147], v[218:221], v[30:33]
	v_mfma_f32_16x16x32_bf16 v[30:33], v[160:163], v[222:225], v[30:33]
	v_mfma_f32_16x16x32_bf16 v[26:29], v[168:171], v[222:225], v[26:29]
	v_mfma_f32_16x16x32_bf16 v[26:29], v[164:167], v[218:221], v[26:29]
	v_mfma_f32_16x16x32_bf16 v[10:13], v[164:167], v[226:229], v[10:13]
	v_mfma_f32_16x16x32_bf16 v[10:13], v[168:171], v[230:233], v[10:13]
	v_mfma_f32_16x16x32_bf16 v[14:17], v[160:163], v[230:233], v[14:17]
	v_mfma_f32_16x16x32_bf16 v[14:17], v[144:147], v[226:229], v[14:17]
	v_mfma_f32_16x16x32_bf16 v[54:57], v[172:175], v[188:191], v[54:57]
	v_mfma_f32_16x16x32_bf16 v[54:57], v[176:179], v[206:209], v[54:57]
	v_mfma_f32_16x16x32_bf16 v[50:53], v[184:187], v[206:209], v[50:53]
	v_mfma_f32_16x16x32_bf16 v[50:53], v[180:183], v[188:191], v[50:53]
	v_mfma_f32_16x16x32_bf16 v[34:37], v[180:183], v[210:213], v[34:37]
	v_mfma_f32_16x16x32_bf16 v[34:37], v[184:187], v[214:217], v[34:37]
	v_mfma_f32_16x16x32_bf16 v[38:41], v[176:179], v[214:217], v[38:41]
	v_mfma_f32_16x16x32_bf16 v[38:41], v[172:175], v[210:213], v[38:41]
	v_mfma_f32_16x16x32_bf16 v[22:25], v[172:175], v[218:221], v[22:25]
	v_mfma_f32_16x16x32_bf16 v[22:25], v[176:179], v[222:225], v[22:25]
	v_mfma_f32_16x16x32_bf16 v[18:21], v[184:187], v[222:225], v[18:21]
	v_mfma_f32_16x16x32_bf16 v[18:21], v[180:183], v[218:221], v[18:21]
	v_mfma_f32_16x16x32_bf16 v[2:5], v[180:183], v[226:229], v[2:5]
	v_mfma_f32_16x16x32_bf16 v[2:5], v[184:187], v[230:233], v[2:5]
	v_mfma_f32_16x16x32_bf16 v[6:9], v[176:179], v[230:233], v[6:9]
	v_mfma_f32_16x16x32_bf16 v[6:9], v[172:175], v[226:229], v[6:9]
	s_barrier
	s_add_i32 s72, 0, 0x18000
	v_add_u32_e32 v153, s72, v150
	s_add_i32 s73, 0, 0x1c000
	ds_read_b128 v[144:147], v153
	ds_read_b128 v[160:163], v153 offset:1024
	ds_read_b128 v[164:167], v153 offset:2048
	ds_read_b128 v[168:171], v153 offset:3072
	v_add_u32_e32 v153, s73, v150
	ds_read_b128 v[172:175], v153
	ds_read_b128 v[176:179], v153 offset:1024
	ds_read_b128 v[180:183], v153 offset:2048
	ds_read_b128 v[184:187], v153 offset:3072
	s_add_u32 s24, s46, 0x40000
	s_addc_u32 s25, s47, 0
	s_mov_b32 m0, s57
	v_lshl_add_u64 v[236:237], s[24:25], 0, v[130:131]
	ds_read_b128 v[188:191], v152 offset:32768
	ds_read_b128 v[206:209], v152 offset:33792
	ds_read_b128 v[210:213], v152 offset:34816
	ds_read_b128 v[214:217], v152 offset:35840
	ds_read_b128 v[218:221], v152 offset:36864
	ds_read_b128 v[222:225], v152 offset:37888
	ds_read_b128 v[226:229], v152 offset:38912
	ds_read_b128 v[230:233], v152 offset:39936
	global_load_lds_dwordx4 v[236:237], off
	v_lshl_add_u64 v[236:237], s[24:25], 0, v[134:135]
	s_mov_b32 m0, s58
	s_nop 0
	global_load_lds_dwordx4 v[236:237], off
	s_waitcnt vmcnt(8)
	s_waitcnt lgkmcnt(0)
	s_barrier
; #define PG8_STAGE(bufoff, gbase, voff) do { _Pragma("unroll") for (int _i = 0; _i < 2; ++_i) \
;         __builtin_amdgcn_global_load_lds((const unsigned*)((const char*)(gbase) + (voff)[_i]), (PG8_LAS unsigned*)(lds + (bufoff) + ldsw + _i * 8192), 16, 0, 0); } while (0)
; #define PG8_LDA(dst, b, h) do { _Pragma("unroll") for (int m = 0; m < 4; ++m) _Pragma("unroll") for (int k = 0; k < 2; ++k) dst[m][k] = *(const PG8_LAS bf16x8*)(lds + PG8_SA(b, h) + aoff + m * 2048 + k * 1024); } while (0)
; #define PG8_MMA(ai, bj, At, Bt) do { __builtin_amdgcn_s_setprio(1); _Pragma("unroll") for (int m = 0; m < 4; ++m) _Pragma("unroll") for (int n = 0; n < 2; ++n) _Pragma("unroll") for (int k = 0; k < 2; ++k) \
;         acc[ai][bj][m][n] = __builtin_amdgcn_mfma_f32_16x16x32_bf16(Bt[n][k], At[m][k], acc[ai][bj][m][n], 0, 0, 0); __builtin_amdgcn_s_setprio(0); } while (0)
; #define PG8_WAIT_V(n) asm volatile("s_waitcnt vmcnt(" #n ")" ::: "memory")
; #define PG8_WAIT_L(n) asm volatile("s_waitcnt lgkmcnt(" #n ")" ::: "memory")
; #define PG8_BAR __builtin_amdgcn_s_barrier()
; #define PG8_SCHED __builtin_amdgcn_sched_barrier(0)
; template <class Epi, class Sched, bool ALIGN_EPI = false, bool SP2 = false>
; __device__ __forceinline__ void gemm_phase(PG8_LAS unsigned char* lds, const Gemm g, const Sched& S, const Epi& E) {
;     ...
;             PG8_WAIT_V(8); PG8_WAIT_L(0); PG8_BAR; PG8_MMA(0, 0, At, B0); PG8_MMA(0, 1, At, B1); PG8_BAR; PG8_SCHED;
;             PG8_LDA(At, 1, 1); PG8_STAGE(PG8_SB(1, 0), b3, voffB); PG8_STAGE(PG8_SB(1, 1), b3 + hstep, voffB); PG8_STAGE(PG8_SA(1, 0), a3, voffA);
;             PG8_WAIT_V(8); PG8_WAIT_L(0); PG8_BAR; PG8_MMA(1, 0, At, B0); PG8_MMA(1, 1, At, B1); PG8_BAR; PG8_SCHED;
	s_waitcnt lgkmcnt(0)
	v_mfma_f32_16x16x32_bf16 v[126:129], v[144:147], v[188:191], v[126:129]
	v_mfma_f32_16x16x32_bf16 v[126:129], v[160:163], v[206:209], v[126:129]
	v_mfma_f32_16x16x32_bf16 v[122:125], v[168:171], v[206:209], v[122:125]
	v_mfma_f32_16x16x32_bf16 v[122:125], v[164:167], v[188:191], v[122:125]
	v_mfma_f32_16x16x32_bf16 v[106:109], v[164:167], v[210:213], v[106:109]
	v_mfma_f32_16x16x32_bf16 v[106:109], v[168:171], v[214:217], v[106:109]
	v_mfma_f32_16x16x32_bf16 v[110:113], v[160:163], v[214:217], v[110:113]
	v_mfma_f32_16x16x32_bf16 v[110:113], v[144:147], v[210:213], v[110:113]
	v_mfma_f32_16x16x32_bf16 v[94:97], v[144:147], v[218:221], v[94:97]
	v_mfma_f32_16x16x32_bf16 v[94:97], v[160:163], v[222:225], v[94:97]
	v_mfma_f32_16x16x32_bf16 v[90:93], v[168:171], v[222:225], v[90:93]
	v_mfma_f32_16x16x32_bf16 v[90:93], v[164:167], v[218:221], v[90:93]
	v_mfma_f32_16x16x32_bf16 v[74:77], v[164:167], v[226:229], v[74:77]
	v_mfma_f32_16x16x32_bf16 v[74:77], v[168:171], v[230:233], v[74:77]
	v_mfma_f32_16x16x32_bf16 v[78:81], v[160:163], v[230:233], v[78:81]
	v_mfma_f32_16x16x32_bf16 v[78:81], v[144:147], v[226:229], v[78:81]
	v_mfma_f32_16x16x32_bf16 v[118:121], v[172:175], v[188:191], v[118:121]
	v_mfma_f32_16x16x32_bf16 v[118:121], v[176:179], v[206:209], v[118:121]
	v_mfma_f32_16x16x32_bf16 v[114:117], v[184:187], v[206:209], v[114:117]
	v_mfma_f32_16x16x32_bf16 v[114:117], v[180:183], v[188:191], v[114:117]
	v_mfma_f32_16x16x32_bf16 v[98:101], v[180:183], v[210:213], v[98:101]
	v_mfma_f32_16x16x32_bf16 v[98:101], v[184:187], v[214:217], v[98:101]
	v_mfma_f32_16x16x32_bf16 v[102:105], v[176:179], v[214:217], v[102:105]
	v_mfma_f32_16x16x32_bf16 v[102:105], v[172:175], v[210:213], v[102:105]
	v_mfma_f32_16x16x32_bf16 v[86:89], v[172:175], v[218:221], v[86:89]
	v_mfma_f32_16x16x32_bf16 v[86:89], v[176:179], v[222:225], v[86:89]
	v_mfma_f32_16x16x32_bf16 v[82:85], v[184:187], v[222:225], v[82:85]
	v_mfma_f32_16x16x32_bf16 v[82:85], v[180:183], v[218:221], v[82:85]
	v_mfma_f32_16x16x32_bf16 v[66:69], v[180:183], v[226:229], v[66:69]
	v_mfma_f32_16x16x32_bf16 v[66:69], v[184:187], v[230:233], v[66:69]
	v_mfma_f32_16x16x32_bf16 v[70:73], v[176:179], v[230:233], v[70:73]
	v_mfma_f32_16x16x32_bf16 v[70:73], v[172:175], v[226:229], v[70:73]
	s_barrier
	s_add_i32 s24, s72, s51
	v_lshl_add_u64 v[148:149], v[148:149], 0, s[38:39]
	s_mov_b32 m0, s24
	ds_read_b128 v[188:191], v152 offset:49152
	ds_read_b128 v[206:209], v152 offset:50176
	ds_read_b128 v[210:213], v152 offset:51200
	ds_read_b128 v[214:217], v152 offset:52224
	ds_read_b128 v[218:221], v152 offset:53248
	ds_read_b128 v[222:225], v152 offset:54272
	ds_read_b128 v[226:229], v152 offset:55296
	ds_read_b128 v[230:233], v152 offset:56320
	global_load_lds_dwordx4 v[148:149], off
	s_add_i32 m0, s24, 0x2000
	s_add_u32 s24, s42, 0x40080
	v_lshl_add_u64 v[148:149], v[234:235], 0, s[38:39]
	s_addc_u32 s25, s43, 0
	s_add_i32 s42, s73, s51
	global_load_lds_dwordx4 v[148:149], off
	v_lshl_add_u64 v[148:149], s[24:25], 0, v[132:133]
	s_mov_b32 m0, s42
	s_nop 0
	global_load_lds_dwordx4 v[148:149], off
	v_lshl_add_u64 v[148:149], s[24:25], 0, v[136:137]
	s_add_i32 m0, s42, 0x2000
	s_nop 0
	global_load_lds_dwordx4 v[148:149], off
	v_lshl_add_u64 v[148:149], s[26:27], 0, v[130:131]
	s_mov_b32 m0, s64
	s_nop 0
	global_load_lds_dwordx4 v[148:149], off
	v_lshl_add_u64 v[148:149], s[26:27], 0, v[134:135]
	s_mov_b32 m0, s65
	s_nop 0
	global_load_lds_dwordx4 v[148:149], off
	s_waitcnt vmcnt(8)
	s_waitcnt lgkmcnt(0)
	s_barrier
	s_waitcnt lgkmcnt(0)
	v_mfma_f32_16x16x32_bf16 v[62:65], v[144:147], v[188:191], v[62:65]
	v_mfma_f32_16x16x32_bf16 v[62:65], v[160:163], v[206:209], v[62:65]
	v_mfma_f32_16x16x32_bf16 v[58:61], v[168:171], v[206:209], v[58:61]
	v_mfma_f32_16x16x32_bf16 v[58:61], v[164:167], v[188:191], v[58:61]
	v_mfma_f32_16x16x32_bf16 v[42:45], v[164:167], v[210:213], v[42:45]
	v_mfma_f32_16x16x32_bf16 v[42:45], v[168:171], v[214:217], v[42:45]
	v_mfma_f32_16x16x32_bf16 v[46:49], v[160:163], v[214:217], v[46:49]
	v_mfma_f32_16x16x32_bf16 v[46:49], v[144:147], v[210:213], v[46:49]
	v_mfma_f32_16x16x32_bf16 v[30:33], v[144:147], v[218:221], v[30:33]
	v_mfma_f32_16x16x32_bf16 v[30:33], v[160:163], v[222:225], v[30:33]
	v_mfma_f32_16x16x32_bf16 v[26:29], v[168:171], v[222:225], v[26:29]
	v_mfma_f32_16x16x32_bf16 v[26:29], v[164:167], v[218:221], v[26:29]
	v_mfma_f32_16x16x32_bf16 v[10:13], v[164:167], v[226:229], v[10:13]
	v_mfma_f32_16x16x32_bf16 v[10:13], v[168:171], v[230:233], v[10:13]
	v_mfma_f32_16x16x32_bf16 v[14:17], v[160:163], v[230:233], v[14:17]
	v_mfma_f32_16x16x32_bf16 v[14:17], v[144:147], v[226:229], v[14:17]
	v_mfma_f32_16x16x32_bf16 v[54:57], v[172:175], v[188:191], v[54:57]
	v_mfma_f32_16x16x32_bf16 v[54:57], v[176:179], v[206:209], v[54:57]
	v_mfma_f32_16x16x32_bf16 v[50:53], v[184:187], v[206:209], v[50:53]
	v_mfma_f32_16x16x32_bf16 v[50:53], v[180:183], v[188:191], v[50:53]
	v_mfma_f32_16x16x32_bf16 v[34:37], v[180:183], v[210:213], v[34:37]
	v_mfma_f32_16x16x32_bf16 v[34:37], v[184:187], v[214:217], v[34:37]
	v_mfma_f32_16x16x32_bf16 v[38:41], v[176:179], v[214:217], v[38:41]
	v_mfma_f32_16x16x32_bf16 v[38:41], v[172:175], v[210:213], v[38:41]
	v_mfma_f32_16x16x32_bf16 v[22:25], v[172:175], v[218:221], v[22:25]
	v_mfma_f32_16x16x32_bf16 v[22:25], v[176:179], v[222:225], v[22:25]
	v_mfma_f32_16x16x32_bf16 v[18:21], v[184:187], v[222:225], v[18:21]
	v_mfma_f32_16x16x32_bf16 v[18:21], v[180:183], v[218:221], v[18:21]
	v_mfma_f32_16x16x32_bf16 v[2:5], v[180:183], v[226:229], v[2:5]
	v_mfma_f32_16x16x32_bf16 v[2:5], v[184:187], v[230:233], v[2:5]
	v_mfma_f32_16x16x32_bf16 v[6:9], v[176:179], v[230:233], v[6:9]
	v_mfma_f32_16x16x32_bf16 v[6:9], v[172:175], v[226:229], v[6:9]
	s_barrier
	s_add_i32 s71, s71, 2
	s_add_u32 s69, s69, 0x100
	s_addc_u32 s70, s70, 0
	s_cmp_gt_u32 s71, 13
	s_mov_b64 s[24:25], s[2:3]
	s_cbranch_scc0 .LBB0_238
	s_setprio 0
	s_and_b64 vcc, exec, s[6:7]
	s_cbranch_vccz .LBB0_241
	s_barrier

; #define PG8_STAGE(bufoff, gbase, voff) do { _Pragma("unroll") for (int _i = 0; _i < 2; ++_i) \
;         __builtin_amdgcn_global_load_lds((const unsigned*)((const char*)(gbase) + (voff)[_i]), (PG8_LAS unsigned*)(lds + (bufoff) + ldsw + _i * 8192), 16, 0, 0); } while (0)
; #define PG8_LDA(dst, b, h) do { _Pragma("unroll") for (int m = 0; m < 4; ++m) _Pragma("unroll") for (int k = 0; k < 2; ++k) dst[m][k] = *(const PG8_LAS bf16x8*)(lds + PG8_SA(b, h) + aoff + m * 2048 + k * 1024); } while (0)
; #define PG8_LDB(dst, b, h) do { _Pragma("unroll") for (int n = 0; n < 2; ++n) _Pragma("unroll") for (int k = 0; k < 2; ++k) dst[n][k] = *(const PG8_LAS bf16x8*)(lds + PG8_SB(b, h) + boff + n * 2048 + k * 1024); } while (0)
; #define PG8_MMA(ai, bj, At, Bt) do { __builtin_amdgcn_s_setprio(1); _Pragma("unroll") for (int m = 0; m < 4; ++m) _Pragma("unroll") for (int n = 0; n < 2; ++n) _Pragma("unroll") for (int k = 0; k < 2; ++k) \
;         acc[ai][bj][m][n] = __builtin_amdgcn_mfma_f32_16x16x32_bf16(Bt[n][k], At[m][k], acc[ai][bj][m][n], 0, 0, 0); __builtin_amdgcn_s_setprio(0); } while (0)
; #define PG8_WAIT_V(n) asm volatile("s_waitcnt vmcnt(" #n ")" ::: "memory")
; #define PG8_WAIT_L(n) asm volatile("s_waitcnt lgkmcnt(" #n ")" ::: "memory")
; #define PG8_BAR __builtin_amdgcn_s_barrier()
; template <class Epi, class Sched, bool ALIGN_EPI = false, bool SP2 = false>
; __device__ __forceinline__ void gemm_phase(PG8_LAS unsigned char* lds, const Gemm g, const Sched& S, const Epi& E) {
;     ...
;         const char* nA = has_next ? (const char*)g.A + (size_t)nxt.pm * tstep : cA; const char* nB = has_next ? (const char*)g.Bt + (size_t)nxt.pn * tstep : cB;
;         for (int t = 0; t < nt; t += 2) {
;             const bool last = (t == nt - 2);
;             const char* a1 = cA + (size_t)(t + 1) * kstepA;
;             const char* a2 = last ? nA : cA + (size_t)(t + 2) * kstepA; const char* b2 = last ? nB : cB + (size_t)(t + 2) * kstep;
;             const char* a3 = a2 + kstepA; const char* b3 = b2 + kstep;
;             if (last && has_next) S.a_ready(nxt);
;             if constexpr (SP2) {
;             PG8_LDB(B0, 0, 0); PG8_LDB(B1, 0, 1); PG8_SCHED; PG8_LDA(At, 0, 0); PG8_STAGE(PG8_SA(1, 1), a1 + hstep, voffA);
;             PG8_WAIT_V(8); PG8_WAIT_L(0); PG8_BAR; PG8_MMA(0, 0, At, B0); PG8_MMA(0, 1, At, B1); PG8_BAR; PG8_SCHED;
.LBB0_309:
	s_add_u32 s47, s24, 0x100
	s_addc_u32 s48, s25, 0
	s_add_u32 s2, s26, 0x4000
	v_mov_b64_e32 v[2:3], 0
	v_mov_b64_e32 v[4:5], 0
	v_mov_b64_e32 v[6:7], 0
	v_mov_b64_e32 v[8:9], 0
	v_mov_b64_e32 v[10:11], 0
	v_mov_b64_e32 v[12:13], 0
	v_mov_b64_e32 v[14:15], 0
	v_mov_b64_e32 v[16:17], 0
	v_mov_b64_e32 v[18:19], 0
	v_mov_b64_e32 v[20:21], 0
	v_mov_b64_e32 v[22:23], 0
	v_mov_b64_e32 v[24:25], 0
	v_mov_b64_e32 v[26:27], 0
	v_mov_b64_e32 v[28:29], 0
	v_mov_b64_e32 v[30:31], 0
	v_mov_b64_e32 v[32:33], 0
	v_mov_b64_e32 v[34:35], 0
	v_mov_b64_e32 v[36:37], 0
	v_mov_b64_e32 v[38:39], 0
	v_mov_b64_e32 v[40:41], 0
	v_mov_b64_e32 v[42:43], 0
	v_mov_b64_e32 v[44:45], 0
	v_mov_b64_e32 v[46:47], 0
	v_mov_b64_e32 v[48:49], 0
	v_mov_b64_e32 v[50:51], 0
	v_mov_b64_e32 v[52:53], 0
	v_mov_b64_e32 v[54:55], 0
	v_mov_b64_e32 v[56:57], 0
	v_mov_b64_e32 v[58:59], 0
	v_mov_b64_e32 v[60:61], 0
	v_mov_b64_e32 v[62:63], 0
	v_mov_b64_e32 v[64:65], 0
	v_mov_b64_e32 v[66:67], 0
	v_mov_b64_e32 v[68:69], 0
	v_mov_b64_e32 v[70:71], 0
	v_mov_b64_e32 v[72:73], 0
	v_mov_b64_e32 v[74:75], 0
	v_mov_b64_e32 v[76:77], 0
	v_mov_b64_e32 v[78:79], 0
	v_mov_b64_e32 v[80:81], 0
	v_mov_b64_e32 v[82:83], 0
	v_mov_b64_e32 v[84:85], 0
	v_mov_b64_e32 v[86:87], 0
	v_mov_b64_e32 v[88:89], 0
	v_mov_b64_e32 v[90:91], 0
	v_mov_b64_e32 v[92:93], 0
	v_mov_b64_e32 v[94:95], 0
	v_mov_b64_e32 v[96:97], 0
	v_mov_b64_e32 v[98:99], 0
	v_mov_b64_e32 v[100:101], 0
	v_mov_b64_e32 v[102:103], 0
	v_mov_b64_e32 v[104:105], 0
	v_mov_b64_e32 v[106:107], 0
	v_mov_b64_e32 v[108:109], 0
	v_mov_b64_e32 v[110:111], 0
	v_mov_b64_e32 v[112:113], 0
	v_mov_b64_e32 v[114:115], 0
	v_mov_b64_e32 v[116:117], 0
	v_mov_b64_e32 v[118:119], 0
	v_mov_b64_e32 v[120:121], 0
	v_mov_b64_e32 v[122:123], 0
	v_mov_b64_e32 v[124:125], 0
	v_mov_b64_e32 v[126:127], 0
	v_mov_b64_e32 v[128:129], 0
	s_addc_u32 s3, s27, 0
	s_mov_b32 s24, 0
	s_and_b64 vcc, exec, s[42:43]
	s_cbranch_vccnz .Lp1_skip_2
	s_setprio 1
.Lp1_skip_2:
.LBB0_310:
	s_add_i32 s49, s24, 2
	s_add_u32 s25, s2, 0x4000
	s_addc_u32 s26, s3, 0
	s_cmp_eq_u32 s59, s24
	s_cselect_b32 s27, s9, s26
	s_cselect_b32 s26, s8, s25
	s_cselect_b32 s66, s44, s47
	s_cselect_b32 s67, s45, s48
	s_add_u32 s24, s26, 0x4000
	s_addc_u32 s25, s27, 0
	s_add_i32 s65, 0, 0x14000
	v_add_u32_e32 v142, s76, v187
	v_add_u32_e32 v167, s65, v187
	ds_read_b128 v[130:133], v142
	ds_read_b128 v[134:137], v142 offset:1024
	ds_read_b128 v[138:141], v142 offset:2048
	ds_read_b128 v[142:145], v142 offset:3072
	ds_read_b128 v[146:149], v167
	ds_read_b128 v[150:153], v167 offset:1024
	ds_read_b128 v[206:209], v167 offset:2048
	ds_read_b128 v[210:213], v167 offset:3072
	v_lshl_add_u64 v[184:185], s[2:3], 0, v[182:183]
	s_add_i32 m0, s51, 0xc000
	ds_read_b128 v[214:217], v188
	ds_read_b128 v[218:221], v188 offset:1024
	ds_read_b128 v[222:225], v188 offset:2048
	ds_read_b128 v[226:229], v188 offset:3072
	ds_read_b128 v[230:233], v188 offset:4096
	ds_read_b128 v[234:237], v188 offset:5120
	ds_read_b128 v[238:241], v188 offset:6144
	ds_read_b128 v[242:245], v188 offset:7168
	global_load_lds_dwordx4 v[184:185], off
	v_lshl_add_u64 v[184:185], s[2:3], 0, v[180:181]
	s_add_i32 m0, s51, 0xe000
	s_nop 0
	global_load_lds_dwordx4 v[184:185], off
	s_waitcnt vmcnt(8)
	s_waitcnt lgkmcnt(0)
	s_barrier
	s_waitcnt lgkmcnt(0)
	v_mfma_f32_16x16x32_bf16 v[126:129], v[130:133], v[214:217], v[126:129]
	v_mfma_f32_16x16x32_bf16 v[126:129], v[134:137], v[218:221], v[126:129]
	v_mfma_f32_16x16x32_bf16 v[122:125], v[142:145], v[218:221], v[122:125]
	v_mfma_f32_16x16x32_bf16 v[122:125], v[138:141], v[214:217], v[122:125]
	v_mfma_f32_16x16x32_bf16 v[106:109], v[138:141], v[222:225], v[106:109]
	v_mfma_f32_16x16x32_bf16 v[106:109], v[142:145], v[226:229], v[106:109]
	v_mfma_f32_16x16x32_bf16 v[110:113], v[134:137], v[226:229], v[110:113]
	v_mfma_f32_16x16x32_bf16 v[110:113], v[130:133], v[222:225], v[110:113]
	v_mfma_f32_16x16x32_bf16 v[94:97], v[130:133], v[230:233], v[94:97]
	v_mfma_f32_16x16x32_bf16 v[94:97], v[134:137], v[234:237], v[94:97]
	v_mfma_f32_16x16x32_bf16 v[90:93], v[142:145], v[234:237], v[90:93]
	v_mfma_f32_16x16x32_bf16 v[90:93], v[138:141], v[230:233], v[90:93]
	v_mfma_f32_16x16x32_bf16 v[74:77], v[138:141], v[238:241], v[74:77]
	v_mfma_f32_16x16x32_bf16 v[74:77], v[142:145], v[242:245], v[74:77]
	v_mfma_f32_16x16x32_bf16 v[78:81], v[134:137], v[242:245], v[78:81]
	v_mfma_f32_16x16x32_bf16 v[78:81], v[130:133], v[238:241], v[78:81]
	v_mfma_f32_16x16x32_bf16 v[118:121], v[146:149], v[214:217], v[118:121]
	v_mfma_f32_16x16x32_bf16 v[118:121], v[150:153], v[218:221], v[118:121]
	v_mfma_f32_16x16x32_bf16 v[114:117], v[210:213], v[218:221], v[114:117]
	v_mfma_f32_16x16x32_bf16 v[114:117], v[206:209], v[214:217], v[114:117]
	v_mfma_f32_16x16x32_bf16 v[98:101], v[206:209], v[222:225], v[98:101]
	v_mfma_f32_16x16x32_bf16 v[98:101], v[210:213], v[226:229], v[98:101]
	v_mfma_f32_16x16x32_bf16 v[102:105], v[150:153], v[226:229], v[102:105]
	v_mfma_f32_16x16x32_bf16 v[102:105], v[146:149], v[222:225], v[102:105]
	v_mfma_f32_16x16x32_bf16 v[86:89], v[146:149], v[230:233], v[86:89]
	v_mfma_f32_16x16x32_bf16 v[86:89], v[150:153], v[234:237], v[86:89]
	v_mfma_f32_16x16x32_bf16 v[82:85], v[210:213], v[234:237], v[82:85]
	v_mfma_f32_16x16x32_bf16 v[82:85], v[206:209], v[230:233], v[82:85]
	v_mfma_f32_16x16x32_bf16 v[66:69], v[206:209], v[238:241], v[66:69]
	v_mfma_f32_16x16x32_bf16 v[66:69], v[210:213], v[242:245], v[66:69]
	v_mfma_f32_16x16x32_bf16 v[70:73], v[150:153], v[242:245], v[70:73]
	v_mfma_f32_16x16x32_bf16 v[70:73], v[146:149], v[238:241], v[70:73]
	s_barrier
; #define PG8_STAGE(bufoff, gbase, voff) do { _Pragma("unroll") for (int _i = 0; _i < 2; ++_i) \
;         __builtin_amdgcn_global_load_lds((const unsigned*)((const char*)(gbase) + (voff)[_i]), (PG8_LAS unsigned*)(lds + (bufoff) + ldsw + _i * 8192), 16, 0, 0); } while (0)
; #define PG8_LDA(dst, b, h) do { _Pragma("unroll") for (int m = 0; m < 4; ++m) _Pragma("unroll") for (int k = 0; k < 2; ++k) dst[m][k] = *(const PG8_LAS bf16x8*)(lds + PG8_SA(b, h) + aoff + m * 2048 + k * 1024); } while (0)
; #define PG8_LDB(dst, b, h) do { _Pragma("unroll") for (int n = 0; n < 2; ++n) _Pragma("unroll") for (int k = 0; k < 2; ++k) dst[n][k] = *(const PG8_LAS bf16x8*)(lds + PG8_SB(b, h) + boff + n * 2048 + k * 1024); } while (0)
; #define PG8_MMA(ai, bj, At, Bt) do { __builtin_amdgcn_s_setprio(1); _Pragma("unroll") for (int m = 0; m < 4; ++m) _Pragma("unroll") for (int n = 0; n < 2; ++n) _Pragma("unroll") for (int k = 0; k < 2; ++k) \
;         acc[ai][bj][m][n] = __builtin_amdgcn_mfma_f32_16x16x32_bf16(Bt[n][k], At[m][k], acc[ai][bj][m][n], 0, 0, 0); __builtin_amdgcn_s_setprio(0); } while (0)
; #define PG8_WAIT_V(n) asm volatile("s_waitcnt vmcnt(" #n ")" ::: "memory")
; #define PG8_WAIT_L(n) asm volatile("s_waitcnt lgkmcnt(" #n ")" ::: "memory")
; #define PG8_BAR __builtin_amdgcn_s_barrier()
; #define PG8_SCHED __builtin_amdgcn_sched_barrier(0)
; template <class Epi, class Sched, bool ALIGN_EPI = false, bool SP2 = false>
; __device__ __forceinline__ void gemm_phase(PG8_LAS unsigned char* lds, const Gemm g, const Sched& S, const Epi& E) {
;     ...
;             PG8_LDA(At, 0, 1); PG8_STAGE(PG8_SB(0, 0), b2, voffB); PG8_STAGE(PG8_SB(0, 1), b2 + hstep, voffB); PG8_STAGE(PG8_SA(0, 0), a2, voffA);
;             PG8_WAIT_V(8); PG8_WAIT_L(0); PG8_BAR; PG8_MMA(1, 0, At, B0); PG8_MMA(1, 1, At, B1); PG8_BAR; PG8_SCHED;
;             PG8_LDB(B0, 1, 0); PG8_LDB(B1, 1, 1); PG8_SCHED; PG8_LDA(At, 1, 0); PG8_STAGE(PG8_SA(0, 1), a2 + hstep, voffA);
;             PG8_WAIT_V(8); PG8_WAIT_L(0); PG8_BAR; PG8_MMA(0, 0, At, B0); PG8_MMA(0, 1, At, B1); PG8_BAR; PG8_SCHED;
	s_add_i32 s68, s76, s50
	v_lshl_add_u64 v[184:185], s[66:67], 0, v[0:1]
	s_mov_b32 m0, s68
	ds_read_b128 v[214:217], v188 offset:16384
	ds_read_b128 v[218:221], v188 offset:17408
	ds_read_b128 v[222:225], v188 offset:18432
	ds_read_b128 v[226:229], v188 offset:19456
	ds_read_b128 v[230:233], v188 offset:20480
	ds_read_b128 v[234:237], v188 offset:21504
	ds_read_b128 v[238:241], v188 offset:22528
	ds_read_b128 v[242:245], v188 offset:23552
	global_load_lds_dwordx4 v[184:185], off
	s_add_i32 m0, s68, 0x2000
	v_lshl_add_u64 v[190:191], s[66:67], 0, v[164:165]
	s_add_u32 s66, s66, s12
	s_addc_u32 s67, s67, 0
	s_add_i32 s65, s65, s50
	global_load_lds_dwordx4 v[190:191], off
	v_lshl_add_u64 v[246:247], s[66:67], 0, v[0:1]
	s_mov_b32 m0, s65
	v_lshl_add_u64 v[248:249], s[66:67], 0, v[164:165]
	global_load_lds_dwordx4 v[246:247], off
	s_add_i32 m0, s65, 0x2000
	v_lshl_add_u64 v[250:251], s[26:27], 0, v[160:161]
	global_load_lds_dwordx4 v[248:249], off
	s_mov_b32 m0, s51
	s_nop 0
	global_load_lds_dwordx4 v[250:251], off
	v_lshl_add_u64 v[250:251], s[26:27], 0, v[162:163]
	s_mov_b32 m0, s52
	s_nop 0
	global_load_lds_dwordx4 v[250:251], off
	s_waitcnt vmcnt(8)
	s_waitcnt lgkmcnt(0)
	s_barrier
	s_waitcnt lgkmcnt(0)
	v_mfma_f32_16x16x32_bf16 v[62:65], v[130:133], v[214:217], v[62:65]
	v_mfma_f32_16x16x32_bf16 v[62:65], v[134:137], v[218:221], v[62:65]
	v_mfma_f32_16x16x32_bf16 v[58:61], v[142:145], v[218:221], v[58:61]
	v_mfma_f32_16x16x32_bf16 v[58:61], v[138:141], v[214:217], v[58:61]
	v_mfma_f32_16x16x32_bf16 v[42:45], v[138:141], v[222:225], v[42:45]
	v_mfma_f32_16x16x32_bf16 v[42:45], v[142:145], v[226:229], v[42:45]
	v_mfma_f32_16x16x32_bf16 v[46:49], v[134:137], v[226:229], v[46:49]
	v_mfma_f32_16x16x32_bf16 v[46:49], v[130:133], v[222:225], v[46:49]
	v_mfma_f32_16x16x32_bf16 v[30:33], v[130:133], v[230:233], v[30:33]
	v_mfma_f32_16x16x32_bf16 v[30:33], v[134:137], v[234:237], v[30:33]
	v_mfma_f32_16x16x32_bf16 v[26:29], v[142:145], v[234:237], v[26:29]
	v_mfma_f32_16x16x32_bf16 v[26:29], v[138:141], v[230:233], v[26:29]
	v_mfma_f32_16x16x32_bf16 v[10:13], v[138:141], v[238:241], v[10:13]
	v_mfma_f32_16x16x32_bf16 v[10:13], v[142:145], v[242:245], v[10:13]
	v_mfma_f32_16x16x32_bf16 v[14:17], v[134:137], v[242:245], v[14:17]
	v_mfma_f32_16x16x32_bf16 v[14:17], v[130:133], v[238:241], v[14:17]
	v_mfma_f32_16x16x32_bf16 v[54:57], v[146:149], v[214:217], v[54:57]
	v_mfma_f32_16x16x32_bf16 v[54:57], v[150:153], v[218:221], v[54:57]
	v_mfma_f32_16x16x32_bf16 v[50:53], v[210:213], v[218:221], v[50:53]
	v_mfma_f32_16x16x32_bf16 v[50:53], v[206:209], v[214:217], v[50:53]
	v_mfma_f32_16x16x32_bf16 v[34:37], v[206:209], v[222:225], v[34:37]
	v_mfma_f32_16x16x32_bf16 v[34:37], v[210:213], v[226:229], v[34:37]
	v_mfma_f32_16x16x32_bf16 v[38:41], v[150:153], v[226:229], v[38:41]
	v_mfma_f32_16x16x32_bf16 v[38:41], v[146:149], v[222:225], v[38:41]
	v_mfma_f32_16x16x32_bf16 v[22:25], v[146:149], v[230:233], v[22:25]
	v_mfma_f32_16x16x32_bf16 v[22:25], v[150:153], v[234:237], v[22:25]
	v_mfma_f32_16x16x32_bf16 v[18:21], v[210:213], v[234:237], v[18:21]
	v_mfma_f32_16x16x32_bf16 v[18:21], v[206:209], v[230:233], v[18:21]
	v_mfma_f32_16x16x32_bf16 v[2:5], v[206:209], v[238:241], v[2:5]
	v_mfma_f32_16x16x32_bf16 v[2:5], v[210:213], v[242:245], v[2:5]
	v_mfma_f32_16x16x32_bf16 v[6:9], v[150:153], v[242:245], v[6:9]
	v_mfma_f32_16x16x32_bf16 v[6:9], v[146:149], v[238:241], v[6:9]
	s_barrier
	s_add_i32 s65, 0, 0x18000
	s_add_i32 s66, 0, 0x1c000
	v_add_u32_e32 v142, s65, v187
	v_add_u32_e32 v167, s66, v187
	ds_read_b128 v[130:133], v142
	ds_read_b128 v[134:137], v142 offset:1024
	ds_read_b128 v[138:141], v142 offset:2048
	ds_read_b128 v[142:145], v142 offset:3072
	ds_read_b128 v[146:149], v167
	ds_read_b128 v[150:153], v167 offset:1024
	ds_read_b128 v[206:209], v167 offset:2048
	ds_read_b128 v[210:213], v167 offset:3072
	s_add_u32 s26, s26, s12
	s_addc_u32 s27, s27, 0
	s_mov_b32 m0, s53
	v_lshl_add_u64 v[250:251], s[26:27], 0, v[160:161]
	ds_read_b128 v[214:217], v188 offset:32768
	ds_read_b128 v[218:221], v188 offset:33792
	ds_read_b128 v[222:225], v188 offset:34816
	ds_read_b128 v[226:229], v188 offset:35840
	ds_read_b128 v[230:233], v188 offset:36864
	ds_read_b128 v[234:237], v188 offset:37888
	ds_read_b128 v[238:241], v188 offset:38912
	ds_read_b128 v[242:245], v188 offset:39936
	global_load_lds_dwordx4 v[250:251], off
	v_lshl_add_u64 v[250:251], s[26:27], 0, v[162:163]
	s_mov_b32 m0, s54
	s_nop 0
	global_load_lds_dwordx4 v[250:251], off
	s_waitcnt vmcnt(8)
	s_waitcnt lgkmcnt(0)
	s_barrier
; #define PG8_STAGE(bufoff, gbase, voff) do { _Pragma("unroll") for (int _i = 0; _i < 2; ++_i) \
;         __builtin_amdgcn_global_load_lds((const unsigned*)((const char*)(gbase) + (voff)[_i]), (PG8_LAS unsigned*)(lds + (bufoff) + ldsw + _i * 8192), 16, 0, 0); } while (0)
; #define PG8_LDA(dst, b, h) do { _Pragma("unroll") for (int m = 0; m < 4; ++m) _Pragma("unroll") for (int k = 0; k < 2; ++k) dst[m][k] = *(const PG8_LAS bf16x8*)(lds + PG8_SA(b, h) + aoff + m * 2048 + k * 1024); } while (0)
; #define PG8_MMA(ai, bj, At, Bt) do { __builtin_amdgcn_s_setprio(1); _Pragma("unroll") for (int m = 0; m < 4; ++m) _Pragma("unroll") for (int n = 0; n < 2; ++n) _Pragma("unroll") for (int k = 0; k < 2; ++k) \
;         acc[ai][bj][m][n] = __builtin_amdgcn_mfma_f32_16x16x32_bf16(Bt[n][k], At[m][k], acc[ai][bj][m][n], 0, 0, 0); __builtin_amdgcn_s_setprio(0); } while (0)
; #define PG8_WAIT_V(n) asm volatile("s_waitcnt vmcnt(" #n ")" ::: "memory")
; #define PG8_WAIT_L(n) asm volatile("s_waitcnt lgkmcnt(" #n ")" ::: "memory")
; #define PG8_BAR __builtin_amdgcn_s_barrier()
; #define PG8_SCHED __builtin_amdgcn_sched_barrier(0)
; template <class Epi, class Sched, bool ALIGN_EPI = false, bool SP2 = false>
; __device__ __forceinline__ void gemm_phase(PG8_LAS unsigned char* lds, const Gemm g, const Sched& S, const Epi& E) {
;     ...
;             PG8_WAIT_V(8); PG8_WAIT_L(0); PG8_BAR; PG8_MMA(0, 0, At, B0); PG8_MMA(0, 1, At, B1); PG8_BAR; PG8_SCHED;
;             PG8_LDA(At, 1, 1); PG8_STAGE(PG8_SB(1, 0), b3, voffB); PG8_STAGE(PG8_SB(1, 1), b3 + hstep, voffB); PG8_STAGE(PG8_SA(1, 0), a3, voffA);
;             PG8_WAIT_V(8); PG8_WAIT_L(0); PG8_BAR; PG8_MMA(1, 0, At, B0); PG8_MMA(1, 1, At, B1); PG8_BAR; PG8_SCHED;
	s_waitcnt lgkmcnt(0)
	v_mfma_f32_16x16x32_bf16 v[126:129], v[130:133], v[214:217], v[126:129]
	v_mfma_f32_16x16x32_bf16 v[126:129], v[134:137], v[218:221], v[126:129]
	v_mfma_f32_16x16x32_bf16 v[122:125], v[142:145], v[218:221], v[122:125]
	v_mfma_f32_16x16x32_bf16 v[122:125], v[138:141], v[214:217], v[122:125]
	v_mfma_f32_16x16x32_bf16 v[106:109], v[138:141], v[222:225], v[106:109]
	v_mfma_f32_16x16x32_bf16 v[106:109], v[142:145], v[226:229], v[106:109]
	v_mfma_f32_16x16x32_bf16 v[110:113], v[134:137], v[226:229], v[110:113]
	v_mfma_f32_16x16x32_bf16 v[110:113], v[130:133], v[222:225], v[110:113]
	v_mfma_f32_16x16x32_bf16 v[94:97], v[130:133], v[230:233], v[94:97]
	v_mfma_f32_16x16x32_bf16 v[94:97], v[134:137], v[234:237], v[94:97]
	v_mfma_f32_16x16x32_bf16 v[90:93], v[142:145], v[234:237], v[90:93]
	v_mfma_f32_16x16x32_bf16 v[90:93], v[138:141], v[230:233], v[90:93]
	v_mfma_f32_16x16x32_bf16 v[74:77], v[138:141], v[238:241], v[74:77]
	v_mfma_f32_16x16x32_bf16 v[74:77], v[142:145], v[242:245], v[74:77]
	v_mfma_f32_16x16x32_bf16 v[78:81], v[134:137], v[242:245], v[78:81]
	v_mfma_f32_16x16x32_bf16 v[78:81], v[130:133], v[238:241], v[78:81]
	v_mfma_f32_16x16x32_bf16 v[118:121], v[146:149], v[214:217], v[118:121]
	v_mfma_f32_16x16x32_bf16 v[118:121], v[150:153], v[218:221], v[118:121]
	v_mfma_f32_16x16x32_bf16 v[114:117], v[210:213], v[218:221], v[114:117]
	v_mfma_f32_16x16x32_bf16 v[114:117], v[206:209], v[214:217], v[114:117]
	v_mfma_f32_16x16x32_bf16 v[98:101], v[206:209], v[222:225], v[98:101]
	v_mfma_f32_16x16x32_bf16 v[98:101], v[210:213], v[226:229], v[98:101]
	v_mfma_f32_16x16x32_bf16 v[102:105], v[150:153], v[226:229], v[102:105]
	v_mfma_f32_16x16x32_bf16 v[102:105], v[146:149], v[222:225], v[102:105]
	v_mfma_f32_16x16x32_bf16 v[86:89], v[146:149], v[230:233], v[86:89]
	v_mfma_f32_16x16x32_bf16 v[86:89], v[150:153], v[234:237], v[86:89]
	v_mfma_f32_16x16x32_bf16 v[82:85], v[210:213], v[234:237], v[82:85]
	v_mfma_f32_16x16x32_bf16 v[82:85], v[206:209], v[230:233], v[82:85]
	v_mfma_f32_16x16x32_bf16 v[66:69], v[206:209], v[238:241], v[66:69]
	v_mfma_f32_16x16x32_bf16 v[66:69], v[210:213], v[242:245], v[66:69]
	v_mfma_f32_16x16x32_bf16 v[70:73], v[150:153], v[242:245], v[70:73]
	v_mfma_f32_16x16x32_bf16 v[70:73], v[146:149], v[238:241], v[70:73]
	s_barrier
	s_add_i32 s26, s65, s50
	v_lshl_add_u64 v[184:185], v[184:185], 0, s[38:39]
	s_mov_b32 m0, s26
	ds_read_b128 v[214:217], v188 offset:49152
	ds_read_b128 v[218:221], v188 offset:50176
	ds_read_b128 v[222:225], v188 offset:51200
	ds_read_b128 v[226:229], v188 offset:52224
	ds_read_b128 v[230:233], v188 offset:53248
	ds_read_b128 v[234:237], v188 offset:54272
	ds_read_b128 v[238:241], v188 offset:55296
	ds_read_b128 v[242:245], v188 offset:56320
	global_load_lds_dwordx4 v[184:185], off
	v_lshl_add_u64 v[184:185], v[190:191], 0, s[38:39]
	s_add_i32 m0, s26, 0x2000
	s_add_i32 s26, s66, s50
	global_load_lds_dwordx4 v[184:185], off
	v_lshl_add_u64 v[184:185], v[246:247], 0, s[38:39]
	s_mov_b32 m0, s26
	s_nop 0
	global_load_lds_dwordx4 v[184:185], off
	v_lshl_add_u64 v[184:185], v[248:249], 0, s[38:39]
	s_add_i32 m0, s26, 0x2000
	s_nop 0
	global_load_lds_dwordx4 v[184:185], off
	v_lshl_add_u64 v[184:185], s[24:25], 0, v[160:161]
	s_mov_b32 m0, s56
	s_nop 0
	global_load_lds_dwordx4 v[184:185], off
	v_lshl_add_u64 v[184:185], s[24:25], 0, v[162:163]
	s_mov_b32 m0, s57
	s_nop 0
	global_load_lds_dwordx4 v[184:185], off
	s_waitcnt vmcnt(8)
	s_waitcnt lgkmcnt(0)
	s_barrier
	s_waitcnt lgkmcnt(0)
	v_mfma_f32_16x16x32_bf16 v[62:65], v[130:133], v[214:217], v[62:65]
	v_mfma_f32_16x16x32_bf16 v[62:65], v[134:137], v[218:221], v[62:65]
	v_mfma_f32_16x16x32_bf16 v[58:61], v[142:145], v[218:221], v[58:61]
	v_mfma_f32_16x16x32_bf16 v[58:61], v[138:141], v[214:217], v[58:61]
	v_mfma_f32_16x16x32_bf16 v[42:45], v[138:141], v[222:225], v[42:45]
	v_mfma_f32_16x16x32_bf16 v[42:45], v[142:145], v[226:229], v[42:45]
	v_mfma_f32_16x16x32_bf16 v[46:49], v[134:137], v[226:229], v[46:49]
	v_mfma_f32_16x16x32_bf16 v[46:49], v[130:133], v[222:225], v[46:49]
	v_mfma_f32_16x16x32_bf16 v[30:33], v[130:133], v[230:233], v[30:33]
	v_mfma_f32_16x16x32_bf16 v[30:33], v[134:137], v[234:237], v[30:33]
	v_mfma_f32_16x16x32_bf16 v[26:29], v[142:145], v[234:237], v[26:29]
	v_mfma_f32_16x16x32_bf16 v[26:29], v[138:141], v[230:233], v[26:29]
	v_mfma_f32_16x16x32_bf16 v[10:13], v[138:141], v[238:241], v[10:13]
	v_mfma_f32_16x16x32_bf16 v[10:13], v[142:145], v[242:245], v[10:13]
	v_mfma_f32_16x16x32_bf16 v[14:17], v[134:137], v[242:245], v[14:17]
	v_mfma_f32_16x16x32_bf16 v[14:17], v[130:133], v[238:241], v[14:17]
	v_mfma_f32_16x16x32_bf16 v[54:57], v[146:149], v[214:217], v[54:57]
	v_mfma_f32_16x16x32_bf16 v[54:57], v[150:153], v[218:221], v[54:57]
	v_mfma_f32_16x16x32_bf16 v[50:53], v[210:213], v[218:221], v[50:53]
	v_mfma_f32_16x16x32_bf16 v[50:53], v[206:209], v[214:217], v[50:53]
	v_mfma_f32_16x16x32_bf16 v[34:37], v[206:209], v[222:225], v[34:37]
	v_mfma_f32_16x16x32_bf16 v[34:37], v[210:213], v[226:229], v[34:37]
	v_mfma_f32_16x16x32_bf16 v[38:41], v[150:153], v[226:229], v[38:41]
	v_mfma_f32_16x16x32_bf16 v[38:41], v[146:149], v[222:225], v[38:41]
	v_mfma_f32_16x16x32_bf16 v[22:25], v[146:149], v[230:233], v[22:25]
	v_mfma_f32_16x16x32_bf16 v[22:25], v[150:153], v[234:237], v[22:25]
	v_mfma_f32_16x16x32_bf16 v[18:21], v[210:213], v[234:237], v[18:21]
	v_mfma_f32_16x16x32_bf16 v[18:21], v[206:209], v[230:233], v[18:21]
	v_mfma_f32_16x16x32_bf16 v[2:5], v[206:209], v[238:241], v[2:5]
	v_mfma_f32_16x16x32_bf16 v[2:5], v[210:213], v[242:245], v[2:5]
	v_mfma_f32_16x16x32_bf16 v[6:9], v[150:153], v[242:245], v[6:9]
	v_mfma_f32_16x16x32_bf16 v[6:9], v[146:149], v[238:241], v[6:9]
	s_barrier
	s_add_u32 s47, s47, 0x100
	s_addc_u32 s48, s48, 0
	s_add_u32 s2, s2, 0x8000
	s_addc_u32 s3, s3, 0
	s_cmp_ge_u32 s49, s55
	s_mov_b32 s24, s49
	s_cbranch_scc0 .LBB0_310
	s_setprio 0
	s_and_b64 vcc, exec, s[42:43]
	s_cbranch_vccz .LBB0_313
	s_barrier

; #define PG8_STAGE(bufoff, gbase, voff) do { _Pragma("unroll") for (int _i = 0; _i < 2; ++_i) \
;         __builtin_amdgcn_global_load_lds((const unsigned*)((const char*)(gbase) + (voff)[_i]), (PG8_LAS unsigned*)(lds + (bufoff) + ldsw + _i * 8192), 16, 0, 0); } while (0)
; #define PG8_LDA(dst, b, h) do { _Pragma("unroll") for (int m = 0; m < 4; ++m) _Pragma("unroll") for (int k = 0; k < 2; ++k) dst[m][k] = *(const PG8_LAS bf16x8*)(lds + PG8_SA(b, h) + aoff + m * 2048 + k * 1024); } while (0)
; #define PG8_LDB(dst, b, h) do { _Pragma("unroll") for (int n = 0; n < 2; ++n) _Pragma("unroll") for (int k = 0; k < 2; ++k) dst[n][k] = *(const PG8_LAS bf16x8*)(lds + PG8_SB(b, h) + boff + n * 2048 + k * 1024); } while (0)
; #define PG8_MMA(ai, bj, At, Bt) do { __builtin_amdgcn_s_setprio(1); _Pragma("unroll") for (int m = 0; m < 4; ++m) _Pragma("unroll") for (int n = 0; n < 2; ++n) _Pragma("unroll") for (int k = 0; k < 2; ++k) \
;         acc[ai][bj][m][n] = __builtin_amdgcn_mfma_f32_16x16x32_bf16(Bt[n][k], At[m][k], acc[ai][bj][m][n], 0, 0, 0); __builtin_amdgcn_s_setprio(0); } while (0)
; #define PG8_WAIT_V(n) asm volatile("s_waitcnt vmcnt(" #n ")" ::: "memory")
; #define PG8_WAIT_L(n) asm volatile("s_waitcnt lgkmcnt(" #n ")" ::: "memory")
; #define PG8_BAR __builtin_amdgcn_s_barrier()
; template <class Epi, class Sched, bool ALIGN_EPI = false, bool SP2 = false>
; __device__ __forceinline__ void gemm_phase(PG8_LAS unsigned char* lds, const Gemm g, const Sched& S, const Epi& E) {
;     ...
;         const char* nA = has_next ? (const char*)g.A + (size_t)nxt.pm * tstep : cA; const char* nB = has_next ? (const char*)g.Bt + (size_t)nxt.pn * tstep : cB;
;         for (int t = 0; t < nt; t += 2) {
;             const bool last = (t == nt - 2);
;             const char* a1 = cA + (size_t)(t + 1) * kstepA;
;             const char* a2 = last ? nA : cA + (size_t)(t + 2) * kstepA; const char* b2 = last ? nB : cB + (size_t)(t + 2) * kstep;
;             const char* a3 = a2 + kstepA; const char* b3 = b2 + kstep;
;             if (last && has_next) S.a_ready(nxt);
;             if constexpr (SP2) {
;             PG8_LDB(B0, 0, 0); PG8_LDB(B1, 0, 1); PG8_SCHED; PG8_LDA(At, 0, 0); PG8_STAGE(PG8_SA(1, 1), a1 + hstep, voffA);
;             PG8_WAIT_V(8); PG8_WAIT_L(0); PG8_BAR; PG8_MMA(0, 0, At, B0); PG8_MMA(0, 1, At, B1); PG8_BAR; PG8_SCHED;
.LBB0_408:
	s_ashr_i32 s11, s10, 31
	s_lshl_b64 s[12:13], s[10:11], 19
	s_add_u32 s12, s30, s12
	s_addc_u32 s13, s31, s13
	s_and_b64 s[18:19], s[4:5], exec
	s_cselect_b32 s11, s13, s23
	s_cselect_b32 s53, s12, s22
	s_ashr_i32 s9, s8, 31
	s_lshl_b64 s[18:19], s[8:9], 19
	s_add_u32 s18, s37, s18
	s_addc_u32 s19, s44, s19
	s_and_b64 s[26:27], s[4:5], exec
	s_cselect_b32 s9, s19, s25
	s_cselect_b32 s54, s18, s24
	s_add_u32 s55, s24, 0x100
	v_mov_b64_e32 v[2:3], 0
	v_mov_b64_e32 v[4:5], 0
	v_mov_b64_e32 v[6:7], 0
	v_mov_b64_e32 v[8:9], 0
	v_mov_b64_e32 v[10:11], 0
	v_mov_b64_e32 v[12:13], 0
	v_mov_b64_e32 v[14:15], 0
	v_mov_b64_e32 v[16:17], 0
	v_mov_b64_e32 v[18:19], 0
	v_mov_b64_e32 v[20:21], 0
	v_mov_b64_e32 v[22:23], 0
	v_mov_b64_e32 v[24:25], 0
	v_mov_b64_e32 v[26:27], 0
	v_mov_b64_e32 v[28:29], 0
	v_mov_b64_e32 v[30:31], 0
	v_mov_b64_e32 v[32:33], 0
	v_mov_b64_e32 v[34:35], 0
	v_mov_b64_e32 v[36:37], 0
	v_mov_b64_e32 v[38:39], 0
	v_mov_b64_e32 v[40:41], 0
	v_mov_b64_e32 v[42:43], 0
	v_mov_b64_e32 v[44:45], 0
	v_mov_b64_e32 v[46:47], 0
	v_mov_b64_e32 v[48:49], 0
	v_mov_b64_e32 v[50:51], 0
	v_mov_b64_e32 v[52:53], 0
	v_mov_b64_e32 v[54:55], 0
	v_mov_b64_e32 v[56:57], 0
	v_mov_b64_e32 v[58:59], 0
	v_mov_b64_e32 v[60:61], 0
	v_mov_b64_e32 v[62:63], 0
	v_mov_b64_e32 v[64:65], 0
	v_mov_b64_e32 v[66:67], 0
	v_mov_b64_e32 v[68:69], 0
	v_mov_b64_e32 v[70:71], 0
	v_mov_b64_e32 v[72:73], 0
	v_mov_b64_e32 v[74:75], 0
	v_mov_b64_e32 v[76:77], 0
	v_mov_b64_e32 v[78:79], 0
	v_mov_b64_e32 v[80:81], 0
	v_mov_b64_e32 v[82:83], 0
	v_mov_b64_e32 v[84:85], 0
	v_mov_b64_e32 v[86:87], 0
	v_mov_b64_e32 v[88:89], 0
	v_mov_b64_e32 v[90:91], 0
	v_mov_b64_e32 v[92:93], 0
	v_mov_b64_e32 v[94:95], 0
	v_mov_b64_e32 v[96:97], 0
	v_mov_b64_e32 v[98:99], 0
	v_mov_b64_e32 v[100:101], 0
	v_mov_b64_e32 v[102:103], 0
	v_mov_b64_e32 v[104:105], 0
	v_mov_b64_e32 v[106:107], 0
	v_mov_b64_e32 v[108:109], 0
	v_mov_b64_e32 v[110:111], 0
	v_mov_b64_e32 v[112:113], 0
	v_mov_b64_e32 v[114:115], 0
	v_mov_b64_e32 v[116:117], 0
	v_mov_b64_e32 v[118:119], 0
	v_mov_b64_e32 v[120:121], 0
	v_mov_b64_e32 v[122:123], 0
	v_mov_b64_e32 v[124:125], 0
	v_mov_b64_e32 v[126:127], 0
	v_mov_b64_e32 v[128:129], 0
	s_addc_u32 s56, s25, 0
	s_mov_b32 s57, -2
	s_and_b64 vcc, exec, s[6:7]
	s_cbranch_vccnz .Lp1_skip_3
	s_setprio 1
.Lp1_skip_3:
.LBB0_409:
	s_add_u32 s24, s22, 0x8000
	s_addc_u32 s25, s23, 0
	s_cmp_eq_u32 s57, 12
	s_cselect_b32 s42, s53, s24
	s_cselect_b32 s43, s11, s25
	s_cselect_b32 s40, s54, s55
	s_cselect_b32 s41, s9, s56
	s_add_u32 s26, s42, 0x4000
	s_addc_u32 s27, s43, 0
	v_add_u32_e32 v145, s76, v142
	s_add_i32 s58, 0, 0x14000
	ds_read_b128 v[146:149], v145
	ds_read_b128 v[150:153], v145 offset:1024
	ds_read_b128 v[160:163], v145 offset:2048
	ds_read_b128 v[164:167], v145 offset:3072
	v_add_u32_e32 v145, s58, v142
	ds_read_b128 v[168:171], v145
	ds_read_b128 v[172:175], v145 offset:1024
	ds_read_b128 v[176:179], v145 offset:2048
	ds_read_b128 v[180:183], v145 offset:3072
	v_lshl_add_u64 v[230:231], s[22:23], 0, v[140:141]
	s_add_i32 m0, s45, 0xc000
	ds_read_b128 v[184:187], v144
	ds_read_b128 v[188:191], v144 offset:1024
	ds_read_b128 v[206:209], v144 offset:2048
	ds_read_b128 v[210:213], v144 offset:3072
	ds_read_b128 v[214:217], v144 offset:4096
	ds_read_b128 v[218:221], v144 offset:5120
	ds_read_b128 v[222:225], v144 offset:6144
	ds_read_b128 v[226:229], v144 offset:7168
	global_load_lds_dwordx4 v[230:231], off
	v_lshl_add_u64 v[230:231], s[22:23], 0, v[138:139]
	s_add_i32 m0, s45, 0xe000
	s_nop 0
	global_load_lds_dwordx4 v[230:231], off
	s_waitcnt vmcnt(8)
	s_waitcnt lgkmcnt(0)
	s_barrier
	s_waitcnt lgkmcnt(0)
	v_mfma_f32_16x16x32_bf16 v[126:129], v[146:149], v[184:187], v[126:129]
	v_mfma_f32_16x16x32_bf16 v[126:129], v[150:153], v[188:191], v[126:129]
	v_mfma_f32_16x16x32_bf16 v[118:121], v[164:167], v[188:191], v[118:121]
	v_mfma_f32_16x16x32_bf16 v[118:121], v[160:163], v[184:187], v[118:121]
	v_mfma_f32_16x16x32_bf16 v[102:105], v[160:163], v[206:209], v[102:105]
	v_mfma_f32_16x16x32_bf16 v[102:105], v[164:167], v[210:213], v[102:105]
	v_mfma_f32_16x16x32_bf16 v[110:113], v[150:153], v[210:213], v[110:113]
	v_mfma_f32_16x16x32_bf16 v[110:113], v[146:149], v[206:209], v[110:113]
	v_mfma_f32_16x16x32_bf16 v[94:97], v[146:149], v[214:217], v[94:97]
	v_mfma_f32_16x16x32_bf16 v[94:97], v[150:153], v[218:221], v[94:97]
	v_mfma_f32_16x16x32_bf16 v[86:89], v[164:167], v[218:221], v[86:89]
	v_mfma_f32_16x16x32_bf16 v[86:89], v[160:163], v[214:217], v[86:89]
	v_mfma_f32_16x16x32_bf16 v[70:73], v[160:163], v[222:225], v[70:73]
	v_mfma_f32_16x16x32_bf16 v[70:73], v[164:167], v[226:229], v[70:73]
	v_mfma_f32_16x16x32_bf16 v[78:81], v[150:153], v[226:229], v[78:81]
	v_mfma_f32_16x16x32_bf16 v[78:81], v[146:149], v[222:225], v[78:81]
	v_mfma_f32_16x16x32_bf16 v[122:125], v[168:171], v[184:187], v[122:125]
	v_mfma_f32_16x16x32_bf16 v[122:125], v[172:175], v[188:191], v[122:125]
	v_mfma_f32_16x16x32_bf16 v[114:117], v[180:183], v[188:191], v[114:117]
	v_mfma_f32_16x16x32_bf16 v[114:117], v[176:179], v[184:187], v[114:117]
	v_mfma_f32_16x16x32_bf16 v[98:101], v[176:179], v[206:209], v[98:101]
	v_mfma_f32_16x16x32_bf16 v[98:101], v[180:183], v[210:213], v[98:101]
	v_mfma_f32_16x16x32_bf16 v[106:109], v[172:175], v[210:213], v[106:109]
	v_mfma_f32_16x16x32_bf16 v[106:109], v[168:171], v[206:209], v[106:109]
	v_mfma_f32_16x16x32_bf16 v[90:93], v[168:171], v[214:217], v[90:93]
	v_mfma_f32_16x16x32_bf16 v[90:93], v[172:175], v[218:221], v[90:93]
	v_mfma_f32_16x16x32_bf16 v[82:85], v[180:183], v[218:221], v[82:85]
	v_mfma_f32_16x16x32_bf16 v[82:85], v[176:179], v[214:217], v[82:85]
	v_mfma_f32_16x16x32_bf16 v[66:69], v[176:179], v[222:225], v[66:69]
	v_mfma_f32_16x16x32_bf16 v[66:69], v[180:183], v[226:229], v[66:69]
	v_mfma_f32_16x16x32_bf16 v[74:77], v[172:175], v[226:229], v[74:77]
	v_mfma_f32_16x16x32_bf16 v[74:77], v[168:171], v[222:225], v[74:77]
	s_barrier
; #define PG8_STAGE(bufoff, gbase, voff) do { _Pragma("unroll") for (int _i = 0; _i < 2; ++_i) \
;         __builtin_amdgcn_global_load_lds((const unsigned*)((const char*)(gbase) + (voff)[_i]), (PG8_LAS unsigned*)(lds + (bufoff) + ldsw + _i * 8192), 16, 0, 0); } while (0)
; #define PG8_LDA(dst, b, h) do { _Pragma("unroll") for (int m = 0; m < 4; ++m) _Pragma("unroll") for (int k = 0; k < 2; ++k) dst[m][k] = *(const PG8_LAS bf16x8*)(lds + PG8_SA(b, h) + aoff + m * 2048 + k * 1024); } while (0)
; #define PG8_LDB(dst, b, h) do { _Pragma("unroll") for (int n = 0; n < 2; ++n) _Pragma("unroll") for (int k = 0; k < 2; ++k) dst[n][k] = *(const PG8_LAS bf16x8*)(lds + PG8_SB(b, h) + boff + n * 2048 + k * 1024); } while (0)
; #define PG8_MMA(ai, bj, At, Bt) do { __builtin_amdgcn_s_setprio(1); _Pragma("unroll") for (int m = 0; m < 4; ++m) _Pragma("unroll") for (int n = 0; n < 2; ++n) _Pragma("unroll") for (int k = 0; k < 2; ++k) \
;         acc[ai][bj][m][n] = __builtin_amdgcn_mfma_f32_16x16x32_bf16(Bt[n][k], At[m][k], acc[ai][bj][m][n], 0, 0, 0); __builtin_amdgcn_s_setprio(0); } while (0)
; #define PG8_WAIT_V(n) asm volatile("s_waitcnt vmcnt(" #n ")" ::: "memory")
; #define PG8_WAIT_L(n) asm volatile("s_waitcnt lgkmcnt(" #n ")" ::: "memory")
; #define PG8_BAR __builtin_amdgcn_s_barrier()
; #define PG8_SCHED __builtin_amdgcn_sched_barrier(0)
; template <class Epi, class Sched, bool ALIGN_EPI = false, bool SP2 = false>
; __device__ __forceinline__ void gemm_phase(PG8_LAS unsigned char* lds, const Gemm g, const Sched& S, const Epi& E) {
;     ...
;             PG8_LDA(At, 0, 1); PG8_STAGE(PG8_SB(0, 0), b2, voffB); PG8_STAGE(PG8_SB(0, 1), b2 + hstep, voffB); PG8_STAGE(PG8_SA(0, 0), a2, voffA);
;             PG8_WAIT_V(8); PG8_WAIT_L(0); PG8_BAR; PG8_MMA(1, 0, At, B0); PG8_MMA(1, 1, At, B1); PG8_BAR; PG8_SCHED;
;             PG8_LDB(B0, 1, 0); PG8_LDB(B1, 1, 1); PG8_SCHED; PG8_LDA(At, 1, 0); PG8_STAGE(PG8_SA(0, 1), a2 + hstep, voffA);
;             PG8_WAIT_V(8); PG8_WAIT_L(0); PG8_BAR; PG8_MMA(0, 0, At, B0); PG8_MMA(0, 1, At, B1); PG8_BAR; PG8_SCHED;
	s_add_i32 s22, s76, s29
	v_lshl_add_u64 v[230:231], s[40:41], 0, v[0:1]
	s_mov_b32 m0, s22
	ds_read_b128 v[184:187], v144 offset:16384
	ds_read_b128 v[188:191], v144 offset:17408
	ds_read_b128 v[206:209], v144 offset:18432
	ds_read_b128 v[210:213], v144 offset:19456
	ds_read_b128 v[214:217], v144 offset:20480
	ds_read_b128 v[218:221], v144 offset:21504
	ds_read_b128 v[222:225], v144 offset:22528
	ds_read_b128 v[226:229], v144 offset:23552
	global_load_lds_dwordx4 v[230:231], off
	s_add_i32 m0, s22, 0x2000
	s_add_u32 s22, s40, 0x40000
	v_lshl_add_u64 v[232:233], s[40:41], 0, v[130:131]
	s_addc_u32 s23, s41, 0
	s_add_i32 s58, s58, s29
	global_load_lds_dwordx4 v[232:233], off
	v_lshl_add_u64 v[234:235], s[22:23], 0, v[0:1]
	s_mov_b32 m0, s58
	s_nop 0
	global_load_lds_dwordx4 v[234:235], off
	v_lshl_add_u64 v[234:235], s[22:23], 0, v[130:131]
	s_add_i32 m0, s58, 0x2000
	s_nop 0
	global_load_lds_dwordx4 v[234:235], off
	v_lshl_add_u64 v[234:235], s[42:43], 0, v[134:135]
	s_mov_b32 m0, s45
	s_nop 0
	global_load_lds_dwordx4 v[234:235], off
	v_lshl_add_u64 v[234:235], s[42:43], 0, v[132:133]
	s_mov_b32 m0, s46
	s_nop 0
	global_load_lds_dwordx4 v[234:235], off
	s_waitcnt vmcnt(8)
	s_waitcnt lgkmcnt(0)
	s_barrier
	s_waitcnt lgkmcnt(0)
	v_mfma_f32_16x16x32_bf16 v[62:65], v[146:149], v[184:187], v[62:65]
	v_mfma_f32_16x16x32_bf16 v[62:65], v[150:153], v[188:191], v[62:65]
	v_mfma_f32_16x16x32_bf16 v[54:57], v[164:167], v[188:191], v[54:57]
	v_mfma_f32_16x16x32_bf16 v[54:57], v[160:163], v[184:187], v[54:57]
	v_mfma_f32_16x16x32_bf16 v[38:41], v[160:163], v[206:209], v[38:41]
	v_mfma_f32_16x16x32_bf16 v[38:41], v[164:167], v[210:213], v[38:41]
	v_mfma_f32_16x16x32_bf16 v[46:49], v[150:153], v[210:213], v[46:49]
	v_mfma_f32_16x16x32_bf16 v[46:49], v[146:149], v[206:209], v[46:49]
	v_mfma_f32_16x16x32_bf16 v[30:33], v[146:149], v[214:217], v[30:33]
	v_mfma_f32_16x16x32_bf16 v[30:33], v[150:153], v[218:221], v[30:33]
	v_mfma_f32_16x16x32_bf16 v[22:25], v[164:167], v[218:221], v[22:25]
	v_mfma_f32_16x16x32_bf16 v[22:25], v[160:163], v[214:217], v[22:25]
	v_mfma_f32_16x16x32_bf16 v[6:9], v[160:163], v[222:225], v[6:9]
	v_mfma_f32_16x16x32_bf16 v[6:9], v[164:167], v[226:229], v[6:9]
	v_mfma_f32_16x16x32_bf16 v[14:17], v[150:153], v[226:229], v[14:17]
	v_mfma_f32_16x16x32_bf16 v[14:17], v[146:149], v[222:225], v[14:17]
	v_mfma_f32_16x16x32_bf16 v[58:61], v[168:171], v[184:187], v[58:61]
	v_mfma_f32_16x16x32_bf16 v[58:61], v[172:175], v[188:191], v[58:61]
	v_mfma_f32_16x16x32_bf16 v[50:53], v[180:183], v[188:191], v[50:53]
	v_mfma_f32_16x16x32_bf16 v[50:53], v[176:179], v[184:187], v[50:53]
	v_mfma_f32_16x16x32_bf16 v[34:37], v[176:179], v[206:209], v[34:37]
	v_mfma_f32_16x16x32_bf16 v[34:37], v[180:183], v[210:213], v[34:37]
	v_mfma_f32_16x16x32_bf16 v[42:45], v[172:175], v[210:213], v[42:45]
	v_mfma_f32_16x16x32_bf16 v[42:45], v[168:171], v[206:209], v[42:45]
	v_mfma_f32_16x16x32_bf16 v[26:29], v[168:171], v[214:217], v[26:29]
	v_mfma_f32_16x16x32_bf16 v[26:29], v[172:175], v[218:221], v[26:29]
	v_mfma_f32_16x16x32_bf16 v[18:21], v[180:183], v[218:221], v[18:21]
	v_mfma_f32_16x16x32_bf16 v[18:21], v[176:179], v[214:217], v[18:21]
	v_mfma_f32_16x16x32_bf16 v[2:5], v[176:179], v[222:225], v[2:5]
	v_mfma_f32_16x16x32_bf16 v[2:5], v[180:183], v[226:229], v[2:5]
	v_mfma_f32_16x16x32_bf16 v[10:13], v[172:175], v[226:229], v[10:13]
	v_mfma_f32_16x16x32_bf16 v[10:13], v[168:171], v[222:225], v[10:13]
	s_barrier
	s_add_i32 s58, 0, 0x18000
	v_add_u32_e32 v145, s58, v142
	s_add_i32 s59, 0, 0x1c000
	ds_read_b128 v[146:149], v145
	ds_read_b128 v[150:153], v145 offset:1024
	ds_read_b128 v[160:163], v145 offset:2048
	ds_read_b128 v[164:167], v145 offset:3072
	v_add_u32_e32 v145, s59, v142
	ds_read_b128 v[168:171], v145
	ds_read_b128 v[172:175], v145 offset:1024
	ds_read_b128 v[176:179], v145 offset:2048
	ds_read_b128 v[180:183], v145 offset:3072
	s_add_u32 s22, s42, 0x40000
	s_addc_u32 s23, s43, 0
	s_mov_b32 m0, s47
	v_lshl_add_u64 v[234:235], s[22:23], 0, v[134:135]
	ds_read_b128 v[184:187], v144 offset:32768
	ds_read_b128 v[188:191], v144 offset:33792
	ds_read_b128 v[206:209], v144 offset:34816
	ds_read_b128 v[210:213], v144 offset:35840
	ds_read_b128 v[214:217], v144 offset:36864
	ds_read_b128 v[218:221], v144 offset:37888
	ds_read_b128 v[222:225], v144 offset:38912
	ds_read_b128 v[226:229], v144 offset:39936
	global_load_lds_dwordx4 v[234:235], off
	v_lshl_add_u64 v[234:235], s[22:23], 0, v[132:133]
	s_mov_b32 m0, s48
	s_nop 0
	global_load_lds_dwordx4 v[234:235], off
	s_waitcnt vmcnt(8)
	s_waitcnt lgkmcnt(0)
	s_barrier
; #define PG8_STAGE(bufoff, gbase, voff) do { _Pragma("unroll") for (int _i = 0; _i < 2; ++_i) \
;         __builtin_amdgcn_global_load_lds((const unsigned*)((const char*)(gbase) + (voff)[_i]), (PG8_LAS unsigned*)(lds + (bufoff) + ldsw + _i * 8192), 16, 0, 0); } while (0)
; #define PG8_LDA(dst, b, h) do { _Pragma("unroll") for (int m = 0; m < 4; ++m) _Pragma("unroll") for (int k = 0; k < 2; ++k) dst[m][k] = *(const PG8_LAS bf16x8*)(lds + PG8_SA(b, h) + aoff + m * 2048 + k * 1024); } while (0)
; #define PG8_MMA(ai, bj, At, Bt) do { __builtin_amdgcn_s_setprio(1); _Pragma("unroll") for (int m = 0; m < 4; ++m) _Pragma("unroll") for (int n = 0; n < 2; ++n) _Pragma("unroll") for (int k = 0; k < 2; ++k) \
;         acc[ai][bj][m][n] = __builtin_amdgcn_mfma_f32_16x16x32_bf16(Bt[n][k], At[m][k], acc[ai][bj][m][n], 0, 0, 0); __builtin_amdgcn_s_setprio(0); } while (0)
; #define PG8_WAIT_V(n) asm volatile("s_waitcnt vmcnt(" #n ")" ::: "memory")
; #define PG8_WAIT_L(n) asm volatile("s_waitcnt lgkmcnt(" #n ")" ::: "memory")
; #define PG8_BAR __builtin_amdgcn_s_barrier()
; #define PG8_SCHED __builtin_amdgcn_sched_barrier(0)
; template <class Epi, class Sched, bool ALIGN_EPI = false, bool SP2 = false>
; __device__ __forceinline__ void gemm_phase(PG8_LAS unsigned char* lds, const Gemm g, const Sched& S, const Epi& E) {
;     ...
;             PG8_WAIT_V(8); PG8_WAIT_L(0); PG8_BAR; PG8_MMA(0, 0, At, B0); PG8_MMA(0, 1, At, B1); PG8_BAR; PG8_SCHED;
;             PG8_LDA(At, 1, 1); PG8_STAGE(PG8_SB(1, 0), b3, voffB); PG8_STAGE(PG8_SB(1, 1), b3 + hstep, voffB); PG8_STAGE(PG8_SA(1, 0), a3, voffA);
;             PG8_WAIT_V(8); PG8_WAIT_L(0); PG8_BAR; PG8_MMA(1, 0, At, B0); PG8_MMA(1, 1, At, B1); PG8_BAR; PG8_SCHED;
	s_waitcnt lgkmcnt(0)
	v_mfma_f32_16x16x32_bf16 v[126:129], v[146:149], v[184:187], v[126:129]
	v_mfma_f32_16x16x32_bf16 v[126:129], v[150:153], v[188:191], v[126:129]
	v_mfma_f32_16x16x32_bf16 v[118:121], v[164:167], v[188:191], v[118:121]
	v_mfma_f32_16x16x32_bf16 v[118:121], v[160:163], v[184:187], v[118:121]
	v_mfma_f32_16x16x32_bf16 v[102:105], v[160:163], v[206:209], v[102:105]
	v_mfma_f32_16x16x32_bf16 v[102:105], v[164:167], v[210:213], v[102:105]
	v_mfma_f32_16x16x32_bf16 v[110:113], v[150:153], v[210:213], v[110:113]
	v_mfma_f32_16x16x32_bf16 v[110:113], v[146:149], v[206:209], v[110:113]
	v_mfma_f32_16x16x32_bf16 v[94:97], v[146:149], v[214:217], v[94:97]
	v_mfma_f32_16x16x32_bf16 v[94:97], v[150:153], v[218:221], v[94:97]
	v_mfma_f32_16x16x32_bf16 v[86:89], v[164:167], v[218:221], v[86:89]
	v_mfma_f32_16x16x32_bf16 v[86:89], v[160:163], v[214:217], v[86:89]
	v_mfma_f32_16x16x32_bf16 v[70:73], v[160:163], v[222:225], v[70:73]
	v_mfma_f32_16x16x32_bf16 v[70:73], v[164:167], v[226:229], v[70:73]
	v_mfma_f32_16x16x32_bf16 v[78:81], v[150:153], v[226:229], v[78:81]
	v_mfma_f32_16x16x32_bf16 v[78:81], v[146:149], v[222:225], v[78:81]
	v_mfma_f32_16x16x32_bf16 v[122:125], v[168:171], v[184:187], v[122:125]
	v_mfma_f32_16x16x32_bf16 v[122:125], v[172:175], v[188:191], v[122:125]
	v_mfma_f32_16x16x32_bf16 v[114:117], v[180:183], v[188:191], v[114:117]
	v_mfma_f32_16x16x32_bf16 v[114:117], v[176:179], v[184:187], v[114:117]
	v_mfma_f32_16x16x32_bf16 v[98:101], v[176:179], v[206:209], v[98:101]
	v_mfma_f32_16x16x32_bf16 v[98:101], v[180:183], v[210:213], v[98:101]
	v_mfma_f32_16x16x32_bf16 v[106:109], v[172:175], v[210:213], v[106:109]
	v_mfma_f32_16x16x32_bf16 v[106:109], v[168:171], v[206:209], v[106:109]
	v_mfma_f32_16x16x32_bf16 v[90:93], v[168:171], v[214:217], v[90:93]
	v_mfma_f32_16x16x32_bf16 v[90:93], v[172:175], v[218:221], v[90:93]
	v_mfma_f32_16x16x32_bf16 v[82:85], v[180:183], v[218:221], v[82:85]
	v_mfma_f32_16x16x32_bf16 v[82:85], v[176:179], v[214:217], v[82:85]
	v_mfma_f32_16x16x32_bf16 v[66:69], v[176:179], v[222:225], v[66:69]
	v_mfma_f32_16x16x32_bf16 v[66:69], v[180:183], v[226:229], v[66:69]
	v_mfma_f32_16x16x32_bf16 v[74:77], v[172:175], v[226:229], v[74:77]
	v_mfma_f32_16x16x32_bf16 v[74:77], v[168:171], v[222:225], v[74:77]
	s_barrier
	s_add_i32 s22, s58, s29
	v_lshl_add_u64 v[230:231], v[230:231], 0, s[38:39]
	s_mov_b32 m0, s22
	ds_read_b128 v[184:187], v144 offset:49152
	ds_read_b128 v[188:191], v144 offset:50176
	ds_read_b128 v[206:209], v144 offset:51200
	ds_read_b128 v[210:213], v144 offset:52224
	ds_read_b128 v[214:217], v144 offset:53248
	ds_read_b128 v[218:221], v144 offset:54272
	ds_read_b128 v[222:225], v144 offset:55296
	ds_read_b128 v[226:229], v144 offset:56320
	global_load_lds_dwordx4 v[230:231], off
	s_add_i32 m0, s22, 0x2000
	s_add_u32 s22, s40, 0x40080
	v_lshl_add_u64 v[230:231], v[232:233], 0, s[38:39]
	s_addc_u32 s23, s41, 0
	s_add_i32 s40, s59, s29
	global_load_lds_dwordx4 v[230:231], off
	v_lshl_add_u64 v[230:231], s[22:23], 0, v[0:1]
	s_mov_b32 m0, s40
	s_nop 0
	global_load_lds_dwordx4 v[230:231], off
	v_lshl_add_u64 v[230:231], s[22:23], 0, v[130:131]
	s_add_i32 m0, s40, 0x2000
	s_nop 0
	global_load_lds_dwordx4 v[230:231], off
	v_lshl_add_u64 v[230:231], s[26:27], 0, v[134:135]
	s_mov_b32 m0, s49
	s_nop 0
	global_load_lds_dwordx4 v[230:231], off
	v_lshl_add_u64 v[230:231], s[26:27], 0, v[132:133]
	s_mov_b32 m0, s50
	s_nop 0
	global_load_lds_dwordx4 v[230:231], off
	s_waitcnt vmcnt(8)
	s_waitcnt lgkmcnt(0)
	s_barrier
	s_waitcnt lgkmcnt(0)
	v_mfma_f32_16x16x32_bf16 v[62:65], v[146:149], v[184:187], v[62:65]
	v_mfma_f32_16x16x32_bf16 v[62:65], v[150:153], v[188:191], v[62:65]
	v_mfma_f32_16x16x32_bf16 v[54:57], v[164:167], v[188:191], v[54:57]
	v_mfma_f32_16x16x32_bf16 v[54:57], v[160:163], v[184:187], v[54:57]
	v_mfma_f32_16x16x32_bf16 v[38:41], v[160:163], v[206:209], v[38:41]
	v_mfma_f32_16x16x32_bf16 v[38:41], v[164:167], v[210:213], v[38:41]
	v_mfma_f32_16x16x32_bf16 v[46:49], v[150:153], v[210:213], v[46:49]
	v_mfma_f32_16x16x32_bf16 v[46:49], v[146:149], v[206:209], v[46:49]
	v_mfma_f32_16x16x32_bf16 v[30:33], v[146:149], v[214:217], v[30:33]
	v_mfma_f32_16x16x32_bf16 v[30:33], v[150:153], v[218:221], v[30:33]
	v_mfma_f32_16x16x32_bf16 v[22:25], v[164:167], v[218:221], v[22:25]
	v_mfma_f32_16x16x32_bf16 v[22:25], v[160:163], v[214:217], v[22:25]
	v_mfma_f32_16x16x32_bf16 v[6:9], v[160:163], v[222:225], v[6:9]
	v_mfma_f32_16x16x32_bf16 v[6:9], v[164:167], v[226:229], v[6:9]
	v_mfma_f32_16x16x32_bf16 v[14:17], v[150:153], v[226:229], v[14:17]
	v_mfma_f32_16x16x32_bf16 v[14:17], v[146:149], v[222:225], v[14:17]
	v_mfma_f32_16x16x32_bf16 v[58:61], v[168:171], v[184:187], v[58:61]
	v_mfma_f32_16x16x32_bf16 v[58:61], v[172:175], v[188:191], v[58:61]
	v_mfma_f32_16x16x32_bf16 v[50:53], v[180:183], v[188:191], v[50:53]
	v_mfma_f32_16x16x32_bf16 v[50:53], v[176:179], v[184:187], v[50:53]
	v_mfma_f32_16x16x32_bf16 v[34:37], v[176:179], v[206:209], v[34:37]
	v_mfma_f32_16x16x32_bf16 v[34:37], v[180:183], v[210:213], v[34:37]
	v_mfma_f32_16x16x32_bf16 v[42:45], v[172:175], v[210:213], v[42:45]
	v_mfma_f32_16x16x32_bf16 v[42:45], v[168:171], v[206:209], v[42:45]
	v_mfma_f32_16x16x32_bf16 v[26:29], v[168:171], v[214:217], v[26:29]
	v_mfma_f32_16x16x32_bf16 v[26:29], v[172:175], v[218:221], v[26:29]
	v_mfma_f32_16x16x32_bf16 v[18:21], v[180:183], v[218:221], v[18:21]
	v_mfma_f32_16x16x32_bf16 v[18:21], v[176:179], v[214:217], v[18:21]
	v_mfma_f32_16x16x32_bf16 v[2:5], v[176:179], v[222:225], v[2:5]
	v_mfma_f32_16x16x32_bf16 v[2:5], v[180:183], v[226:229], v[2:5]
	v_mfma_f32_16x16x32_bf16 v[10:13], v[172:175], v[226:229], v[10:13]
	v_mfma_f32_16x16x32_bf16 v[10:13], v[168:171], v[222:225], v[10:13]
	s_barrier
	s_add_i32 s57, s57, 2
	s_add_u32 s55, s55, 0x100
	s_addc_u32 s56, s56, 0
	s_cmp_gt_u32 s57, 13
	s_mov_b64 s[22:23], s[24:25]
	s_cbranch_scc0 .LBB0_409
	s_setprio 0
	s_and_b64 vcc, exec, s[6:7]
	s_cbranch_vccz .LBB0_412
	s_barrier
